# one static s_setprio 1 for waves 0-3 at kernel start, all 144 per-segment s_setprio flips in the GEMM loops deleted
# baseline (speedup 1.0000x reference)
.LBB0_27:
	s_or_b64 exec, exec, s[6:7]
	s_lshr_b32 s91, s33, 6
	s_cmp_lt_u32 s91, 4
	s_cbranch_scc0 .Lprio_done
	s_setprio 1
.Lprio_done:
	s_lshl_b32 s3, s2, 3
	s_add_i32 s66, s91, s3
	s_lshl_b32 s68, s46, 3
	s_cmpk_gt_i32 s66, 0x1fff
	v_mbcnt_lo_u32_b32 v225, -1, 0
	s_cbranch_scc1 .LBB0_32
	v_mbcnt_hi_u32_b32 v0, -1, v225
	v_and_b32_e32 v1, 64, v0
	v_add_u32_e32 v1, 64, v1
	v_xor_b32_e32 v2, 1, v0
	v_cmp_lt_i32_e32 vcc, v2, v1
	s_load_dwordx4 s[8:11], s[0:1], 0x0
	s_ashr_i32 s67, s66, 31
	v_cndmask_b32_e32 v2, v0, v2, vcc
	v_lshlrev_b32_e32 v38, 2, v2
	v_xor_b32_e32 v2, 2, v0
	v_cmp_lt_i32_e32 vcc, v2, v1
	s_ashr_i32 s69, s68, 31
	s_lshl_b64 s[6:7], s[66:67], 2
	v_cndmask_b32_e32 v2, v0, v2, vcc
	v_lshlrev_b32_e32 v39, 2, v2
	v_xor_b32_e32 v2, 4, v0
	v_cmp_lt_i32_e32 vcc, v2, v1
	s_lshl_b64 s[12:13], s[68:69], 2
	s_lshl_b64 s[16:17], s[66:67], 10
	v_cndmask_b32_e32 v2, v0, v2, vcc
	v_lshlrev_b32_e32 v40, 2, v2
	v_xor_b32_e32 v2, 8, v0
	v_cmp_lt_i32_e32 vcc, v2, v1
	v_ashrrev_i32_e32 v69, 31, v68
	s_waitcnt lgkmcnt(0)
	s_add_u32 s10, s10, s16
	v_cndmask_b32_e32 v2, v0, v2, vcc
	v_lshlrev_b32_e32 v41, 2, v2
	v_xor_b32_e32 v2, 16, v0
	v_cmp_lt_i32_e32 vcc, v2, v1
	s_addc_u32 s11, s11, s17
	s_lshl_b64 s[18:19], s[66:67], 9
	v_cndmask_b32_e32 v2, v0, v2, vcc
	v_lshlrev_b32_e32 v42, 2, v2
	v_xor_b32_e32 v2, 32, v0
	v_cmp_lt_i32_e32 vcc, v2, v1
	s_lshl_b64 s[16:17], s[68:69], 10
	s_lshl_b64 s[20:21], s[66:67], 13
	v_cndmask_b32_e32 v0, v0, v2, vcc
	v_lshlrev_b32_e32 v43, 2, v0
	v_lshlrev_b64 v[0:1], 3, v[68:69]
	v_lshl_add_u64 v[2:3], s[18:19], 0, v[0:1]
	s_mov_b64 s[18:19], 0xce00000
	v_lshl_add_u64 v[34:35], v[2:3], 0, s[18:19]
	s_lshl_b64 s[18:19], s[68:69], 9
	s_add_u32 s8, s8, s20
	s_addc_u32 s9, s9, s21
	s_lshl_b64 s[22:23], s[66:67], 12
	v_cmp_eq_u32_e64 s[4:5], 0, v68
	v_lshlrev_b64 v[32:33], 4, v[68:69]
	s_lshl_b64 s[20:21], s[68:69], 13
	v_lshl_add_u64 v[36:37], s[22:23], 0, v[0:1]
	s_lshl_b64 s[22:23], s[68:69], 12
	s_movk_i32 s3, 0x1000
	v_mov_b32_e32 v44, 0
	s_mov_b32 s26, s66
	s_branch .LBB0_30

.LBB0_167:
	ds_read_b128 v[144:147], v151
	ds_read_b128 v[156:159], v151 offset:1024
	ds_read_b128 v[160:163], v151 offset:2048
	ds_read_b128 v[164:167], v151 offset:3072
	ds_read_b128 v[168:171], v152
	ds_read_b128 v[172:175], v152 offset:1024
	ds_read_b128 v[176:179], v152 offset:2048
	ds_read_b128 v[180:183], v152 offset:3072
	s_add_u32 s34, s30, 0xfff80080
	s_addc_u32 s35, s31, -1
	s_cmp_eq_u32 s72, 28
	s_cselect_b32 s37, s25, s35
	s_cselect_b32 s36, s62, s34
	s_cselect_b32 s35, s23, s71
	s_cselect_b32 s34, s63, s70
	v_lshl_add_u64 v[216:217], s[30:31], 0, v[136:137]
	s_add_i32 m0, s39, 0xc000
	ds_read_b128 v[184:187], v153
	ds_read_b128 v[188:191], v153 offset:1024
	ds_read_b128 v[192:195], v153 offset:2048
	ds_read_b128 v[196:199], v153 offset:3072
	ds_read_b128 v[200:203], v153 offset:4096
	ds_read_b128 v[204:207], v153 offset:5120
	ds_read_b128 v[208:211], v153 offset:6144
	ds_read_b128 v[212:215], v153 offset:7168
	global_load_lds_dwordx4 v[216:217], off
	v_lshl_add_u64 v[216:217], s[30:31], 0, v[138:139]
	s_add_i32 m0, s39, 0xe000
	s_nop 0
	global_load_lds_dwordx4 v[216:217], off
	s_waitcnt vmcnt(8)
	s_waitcnt lgkmcnt(0)
	s_barrier
	s_waitcnt lgkmcnt(0)
	v_mfma_f32_16x16x32_bf16 v[124:127], v[144:147], v[184:187], v[124:127]
	v_mfma_f32_16x16x32_bf16 v[120:123], v[160:163], v[184:187], v[120:123]
	v_mfma_f32_16x16x32_bf16 v[116:119], v[144:147], v[192:195], v[116:119]
	v_mfma_f32_16x16x32_bf16 v[100:103], v[160:163], v[192:195], v[100:103]
	v_mfma_f32_16x16x32_bf16 v[92:95], v[144:147], v[200:203], v[92:95]
	v_mfma_f32_16x16x32_bf16 v[84:87], v[160:163], v[200:203], v[84:87]
	v_mfma_f32_16x16x32_bf16 v[76:79], v[144:147], v[208:211], v[76:79]
	v_mfma_f32_16x16x32_bf16 v[68:71], v[160:163], v[208:211], v[68:71]
	v_mfma_f32_16x16x32_bf16 v[124:127], v[156:159], v[188:191], v[124:127]
	v_mfma_f32_16x16x32_bf16 v[120:123], v[164:167], v[188:191], v[120:123]
	v_mfma_f32_16x16x32_bf16 v[116:119], v[156:159], v[196:199], v[116:119]
	v_mfma_f32_16x16x32_bf16 v[100:103], v[164:167], v[196:199], v[100:103]
	v_mfma_f32_16x16x32_bf16 v[92:95], v[156:159], v[204:207], v[92:95]
	v_mfma_f32_16x16x32_bf16 v[84:87], v[164:167], v[204:207], v[84:87]
	v_mfma_f32_16x16x32_bf16 v[76:79], v[156:159], v[212:215], v[76:79]
	v_mfma_f32_16x16x32_bf16 v[68:71], v[164:167], v[212:215], v[68:71]
	v_mfma_f32_16x16x32_bf16 v[112:115], v[168:171], v[184:187], v[112:115]
	v_mfma_f32_16x16x32_bf16 v[108:111], v[176:179], v[184:187], v[108:111]
	v_mfma_f32_16x16x32_bf16 v[104:107], v[168:171], v[192:195], v[104:107]
	v_mfma_f32_16x16x32_bf16 v[96:99], v[176:179], v[192:195], v[96:99]
	v_mfma_f32_16x16x32_bf16 v[88:91], v[168:171], v[200:203], v[88:91]
	v_mfma_f32_16x16x32_bf16 v[80:83], v[176:179], v[200:203], v[80:83]
	v_mfma_f32_16x16x32_bf16 v[72:75], v[168:171], v[208:211], v[72:75]
	v_mfma_f32_16x16x32_bf16 v[64:67], v[176:179], v[208:211], v[64:67]
	v_mfma_f32_16x16x32_bf16 v[112:115], v[172:175], v[188:191], v[112:115]
	v_mfma_f32_16x16x32_bf16 v[108:111], v[180:183], v[188:191], v[108:111]
	v_mfma_f32_16x16x32_bf16 v[104:107], v[172:175], v[196:199], v[104:107]
	v_mfma_f32_16x16x32_bf16 v[96:99], v[180:183], v[196:199], v[96:99]
	v_mfma_f32_16x16x32_bf16 v[88:91], v[172:175], v[204:207], v[88:91]
	v_mfma_f32_16x16x32_bf16 v[80:83], v[180:183], v[204:207], v[80:83]
	v_mfma_f32_16x16x32_bf16 v[72:75], v[172:175], v[212:215], v[72:75]
	v_mfma_f32_16x16x32_bf16 v[64:67], v[180:183], v[212:215], v[64:67]
	s_barrier
	s_add_i32 s73, s60, s3
	v_lshl_add_u64 v[216:217], s[34:35], 0, v[132:133]
	s_mov_b32 m0, s73
	ds_read_b128 v[184:187], v153 offset:16384
	ds_read_b128 v[188:191], v153 offset:17408
	ds_read_b128 v[192:195], v153 offset:18432
	ds_read_b128 v[196:199], v153 offset:19456
	ds_read_b128 v[200:203], v153 offset:20480
	ds_read_b128 v[204:207], v153 offset:21504
	ds_read_b128 v[208:211], v153 offset:22528
	ds_read_b128 v[212:215], v153 offset:23552
	global_load_lds_dwordx4 v[216:217], off
	s_add_i32 m0, s73, 0x2000
	s_add_u32 s74, s34, 0x80000
	v_lshl_add_u64 v[218:219], s[34:35], 0, v[128:129]
	s_addc_u32 s75, s35, 0
	s_add_i32 s73, s61, s3
	global_load_lds_dwordx4 v[218:219], off
	v_lshl_add_u64 v[220:221], s[74:75], 0, v[132:133]
	s_mov_b32 m0, s73
	v_lshl_add_u64 v[222:223], s[36:37], 0, v[130:131]
	global_load_lds_dwordx4 v[220:221], off
	v_lshl_add_u64 v[220:221], s[74:75], 0, v[128:129]
	s_add_i32 m0, s73, 0x2000
	s_nop 0
	global_load_lds_dwordx4 v[220:221], off
	v_lshl_add_u64 v[220:221], s[36:37], 0, v[134:135]
	s_mov_b32 m0, s39
	s_nop 0
	global_load_lds_dwordx4 v[220:221], off
	s_mov_b32 m0, s40
	s_nop 0
	global_load_lds_dwordx4 v[222:223], off
	s_waitcnt vmcnt(8)
	s_waitcnt lgkmcnt(0)
	s_barrier
	s_waitcnt lgkmcnt(0)
	v_mfma_f32_16x16x32_bf16 v[60:63], v[144:147], v[184:187], v[60:63]
	v_mfma_f32_16x16x32_bf16 v[52:55], v[160:163], v[184:187], v[52:55]
	v_mfma_f32_16x16x32_bf16 v[44:47], v[144:147], v[192:195], v[44:47]
	v_mfma_f32_16x16x32_bf16 v[36:39], v[160:163], v[192:195], v[36:39]
	v_mfma_f32_16x16x32_bf16 v[28:31], v[144:147], v[200:203], v[28:31]
	v_mfma_f32_16x16x32_bf16 v[20:23], v[160:163], v[200:203], v[20:23]
	v_mfma_f32_16x16x32_bf16 v[12:15], v[144:147], v[208:211], v[12:15]
	v_mfma_f32_16x16x32_bf16 v[4:7], v[160:163], v[208:211], v[4:7]
	v_mfma_f32_16x16x32_bf16 v[60:63], v[156:159], v[188:191], v[60:63]
	v_mfma_f32_16x16x32_bf16 v[52:55], v[164:167], v[188:191], v[52:55]
	v_mfma_f32_16x16x32_bf16 v[44:47], v[156:159], v[196:199], v[44:47]
	v_mfma_f32_16x16x32_bf16 v[36:39], v[164:167], v[196:199], v[36:39]
	v_mfma_f32_16x16x32_bf16 v[28:31], v[156:159], v[204:207], v[28:31]
	v_mfma_f32_16x16x32_bf16 v[20:23], v[164:167], v[204:207], v[20:23]
	v_mfma_f32_16x16x32_bf16 v[12:15], v[156:159], v[212:215], v[12:15]
	v_mfma_f32_16x16x32_bf16 v[4:7], v[164:167], v[212:215], v[4:7]
	v_mfma_f32_16x16x32_bf16 v[56:59], v[168:171], v[184:187], v[56:59]
	v_mfma_f32_16x16x32_bf16 v[48:51], v[176:179], v[184:187], v[48:51]
	v_mfma_f32_16x16x32_bf16 v[40:43], v[168:171], v[192:195], v[40:43]
	v_mfma_f32_16x16x32_bf16 v[32:35], v[176:179], v[192:195], v[32:35]
	v_mfma_f32_16x16x32_bf16 v[24:27], v[168:171], v[200:203], v[24:27]
	v_mfma_f32_16x16x32_bf16 v[16:19], v[176:179], v[200:203], v[16:19]
	v_mfma_f32_16x16x32_bf16 v[8:11], v[168:171], v[208:211], v[8:11]
	v_mfma_f32_16x16x32_bf16 v[0:3], v[176:179], v[208:211], v[0:3]
	v_mfma_f32_16x16x32_bf16 v[56:59], v[172:175], v[188:191], v[56:59]
	v_mfma_f32_16x16x32_bf16 v[48:51], v[180:183], v[188:191], v[48:51]
	v_mfma_f32_16x16x32_bf16 v[40:43], v[172:175], v[196:199], v[40:43]
	v_mfma_f32_16x16x32_bf16 v[32:35], v[180:183], v[196:199], v[32:35]
	v_mfma_f32_16x16x32_bf16 v[24:27], v[172:175], v[204:207], v[24:27]
	v_mfma_f32_16x16x32_bf16 v[16:19], v[180:183], v[204:207], v[16:19]
	v_mfma_f32_16x16x32_bf16 v[8:11], v[172:175], v[212:215], v[8:11]
	v_mfma_f32_16x16x32_bf16 v[0:3], v[180:183], v[212:215], v[0:3]
	s_barrier
	s_add_i32 s73, 0, 0x18000
	v_add_u32_e32 v155, s73, v149
	s_add_i32 s74, 0, 0x1c000
	ds_read_b128 v[144:147], v155
	ds_read_b128 v[156:159], v155 offset:1024
	ds_read_b128 v[160:163], v155 offset:2048
	ds_read_b128 v[164:167], v155 offset:3072
	v_add_u32_e32 v155, s74, v149
	ds_read_b128 v[168:171], v155
	ds_read_b128 v[172:175], v155 offset:1024
	ds_read_b128 v[176:179], v155 offset:2048
	ds_read_b128 v[180:183], v155 offset:3072
	s_add_u32 s36, s36, 0x80000
	s_addc_u32 s37, s37, 0
	s_mov_b32 m0, s41
	v_lshl_add_u64 v[226:227], s[36:37], 0, v[134:135]
	ds_read_b128 v[184:187], v153 offset:32768
	ds_read_b128 v[188:191], v153 offset:33792
	ds_read_b128 v[192:195], v153 offset:34816
	ds_read_b128 v[196:199], v153 offset:35840
	ds_read_b128 v[200:203], v153 offset:36864
	ds_read_b128 v[204:207], v153 offset:37888
	ds_read_b128 v[208:211], v153 offset:38912
	ds_read_b128 v[212:215], v153 offset:39936
	global_load_lds_dwordx4 v[226:227], off
	v_lshl_add_u64 v[226:227], s[36:37], 0, v[130:131]
	s_mov_b32 m0, s42
	s_nop 0
	global_load_lds_dwordx4 v[226:227], off
	s_waitcnt vmcnt(8)
	s_waitcnt lgkmcnt(0)
	s_barrier
	s_waitcnt lgkmcnt(0)
	v_mfma_f32_16x16x32_bf16 v[124:127], v[144:147], v[184:187], v[124:127]
	v_mfma_f32_16x16x32_bf16 v[120:123], v[160:163], v[184:187], v[120:123]
	v_mfma_f32_16x16x32_bf16 v[116:119], v[144:147], v[192:195], v[116:119]
	v_mfma_f32_16x16x32_bf16 v[100:103], v[160:163], v[192:195], v[100:103]
	v_mfma_f32_16x16x32_bf16 v[92:95], v[144:147], v[200:203], v[92:95]
	v_mfma_f32_16x16x32_bf16 v[84:87], v[160:163], v[200:203], v[84:87]
	v_mfma_f32_16x16x32_bf16 v[76:79], v[144:147], v[208:211], v[76:79]
	v_mfma_f32_16x16x32_bf16 v[68:71], v[160:163], v[208:211], v[68:71]
	v_mfma_f32_16x16x32_bf16 v[124:127], v[156:159], v[188:191], v[124:127]
	v_mfma_f32_16x16x32_bf16 v[120:123], v[164:167], v[188:191], v[120:123]
	v_mfma_f32_16x16x32_bf16 v[116:119], v[156:159], v[196:199], v[116:119]
	v_mfma_f32_16x16x32_bf16 v[100:103], v[164:167], v[196:199], v[100:103]
	v_mfma_f32_16x16x32_bf16 v[92:95], v[156:159], v[204:207], v[92:95]
	v_mfma_f32_16x16x32_bf16 v[84:87], v[164:167], v[204:207], v[84:87]
	v_mfma_f32_16x16x32_bf16 v[76:79], v[156:159], v[212:215], v[76:79]
	v_mfma_f32_16x16x32_bf16 v[68:71], v[164:167], v[212:215], v[68:71]
	v_mfma_f32_16x16x32_bf16 v[112:115], v[168:171], v[184:187], v[112:115]
	v_mfma_f32_16x16x32_bf16 v[108:111], v[176:179], v[184:187], v[108:111]
	v_mfma_f32_16x16x32_bf16 v[104:107], v[168:171], v[192:195], v[104:107]
	v_mfma_f32_16x16x32_bf16 v[96:99], v[176:179], v[192:195], v[96:99]
	v_mfma_f32_16x16x32_bf16 v[88:91], v[168:171], v[200:203], v[88:91]
	v_mfma_f32_16x16x32_bf16 v[80:83], v[176:179], v[200:203], v[80:83]
	v_mfma_f32_16x16x32_bf16 v[72:75], v[168:171], v[208:211], v[72:75]
	v_mfma_f32_16x16x32_bf16 v[64:67], v[176:179], v[208:211], v[64:67]
	v_mfma_f32_16x16x32_bf16 v[112:115], v[172:175], v[188:191], v[112:115]
	v_mfma_f32_16x16x32_bf16 v[108:111], v[180:183], v[188:191], v[108:111]
	v_mfma_f32_16x16x32_bf16 v[104:107], v[172:175], v[196:199], v[104:107]
	v_mfma_f32_16x16x32_bf16 v[96:99], v[180:183], v[196:199], v[96:99]
	v_mfma_f32_16x16x32_bf16 v[88:91], v[172:175], v[204:207], v[88:91]
	v_mfma_f32_16x16x32_bf16 v[80:83], v[180:183], v[204:207], v[80:83]
	v_mfma_f32_16x16x32_bf16 v[72:75], v[172:175], v[212:215], v[72:75]
	v_mfma_f32_16x16x32_bf16 v[64:67], v[180:183], v[212:215], v[64:67]
	s_barrier
	s_add_i32 s36, s73, s3
	v_lshl_add_u64 v[216:217], v[216:217], 0, s[18:19]
	s_mov_b32 m0, s36
	ds_read_b128 v[184:187], v153 offset:49152
	ds_read_b128 v[188:191], v153 offset:50176
	ds_read_b128 v[192:195], v153 offset:51200
	ds_read_b128 v[196:199], v153 offset:52224
	ds_read_b128 v[200:203], v153 offset:53248
	ds_read_b128 v[204:207], v153 offset:54272
	ds_read_b128 v[208:211], v153 offset:55296
	ds_read_b128 v[212:215], v153 offset:56320
	global_load_lds_dwordx4 v[216:217], off
	s_add_i32 m0, s36, 0x2000
	s_add_u32 s34, s34, 0x80080
	v_lshl_add_u64 v[216:217], v[218:219], 0, s[18:19]
	s_addc_u32 s35, s35, 0
	s_add_i32 s36, s74, s3
	global_load_lds_dwordx4 v[216:217], off
	v_lshl_add_u64 v[216:217], s[34:35], 0, v[132:133]
	s_mov_b32 m0, s36
	s_nop 0
	global_load_lds_dwordx4 v[216:217], off
	v_lshl_add_u64 v[216:217], s[34:35], 0, v[128:129]
	s_add_i32 m0, s36, 0x2000
	s_nop 0
	global_load_lds_dwordx4 v[216:217], off
	v_lshl_add_u64 v[216:217], v[220:221], 0, s[18:19]
	s_mov_b32 m0, s44
	s_nop 0
	global_load_lds_dwordx4 v[216:217], off
	v_lshl_add_u64 v[216:217], v[222:223], 0, s[18:19]
	s_mov_b32 m0, s45
	s_nop 0
	global_load_lds_dwordx4 v[216:217], off
	s_waitcnt vmcnt(8)
	s_waitcnt lgkmcnt(0)
	s_barrier
	s_waitcnt lgkmcnt(0)
	v_mfma_f32_16x16x32_bf16 v[60:63], v[144:147], v[184:187], v[60:63]
	v_mfma_f32_16x16x32_bf16 v[52:55], v[160:163], v[184:187], v[52:55]
	v_mfma_f32_16x16x32_bf16 v[44:47], v[144:147], v[192:195], v[44:47]
	v_mfma_f32_16x16x32_bf16 v[36:39], v[160:163], v[192:195], v[36:39]
	v_mfma_f32_16x16x32_bf16 v[28:31], v[144:147], v[200:203], v[28:31]
	v_mfma_f32_16x16x32_bf16 v[20:23], v[160:163], v[200:203], v[20:23]
	v_mfma_f32_16x16x32_bf16 v[12:15], v[144:147], v[208:211], v[12:15]
	v_mfma_f32_16x16x32_bf16 v[4:7], v[160:163], v[208:211], v[4:7]
	v_mfma_f32_16x16x32_bf16 v[60:63], v[156:159], v[188:191], v[60:63]
	v_mfma_f32_16x16x32_bf16 v[52:55], v[164:167], v[188:191], v[52:55]
	v_mfma_f32_16x16x32_bf16 v[44:47], v[156:159], v[196:199], v[44:47]
	v_mfma_f32_16x16x32_bf16 v[36:39], v[164:167], v[196:199], v[36:39]
	v_mfma_f32_16x16x32_bf16 v[28:31], v[156:159], v[204:207], v[28:31]
	v_mfma_f32_16x16x32_bf16 v[20:23], v[164:167], v[204:207], v[20:23]
	v_mfma_f32_16x16x32_bf16 v[12:15], v[156:159], v[212:215], v[12:15]
	v_mfma_f32_16x16x32_bf16 v[4:7], v[164:167], v[212:215], v[4:7]
	v_mfma_f32_16x16x32_bf16 v[56:59], v[168:171], v[184:187], v[56:59]
	v_mfma_f32_16x16x32_bf16 v[48:51], v[176:179], v[184:187], v[48:51]
	v_mfma_f32_16x16x32_bf16 v[40:43], v[168:171], v[192:195], v[40:43]
	v_mfma_f32_16x16x32_bf16 v[32:35], v[176:179], v[192:195], v[32:35]
	v_mfma_f32_16x16x32_bf16 v[24:27], v[168:171], v[200:203], v[24:27]
	v_mfma_f32_16x16x32_bf16 v[16:19], v[176:179], v[200:203], v[16:19]
	v_mfma_f32_16x16x32_bf16 v[8:11], v[168:171], v[208:211], v[8:11]
	v_mfma_f32_16x16x32_bf16 v[0:3], v[176:179], v[208:211], v[0:3]
	v_mfma_f32_16x16x32_bf16 v[56:59], v[172:175], v[188:191], v[56:59]
	v_mfma_f32_16x16x32_bf16 v[48:51], v[180:183], v[188:191], v[48:51]
	v_mfma_f32_16x16x32_bf16 v[40:43], v[172:175], v[196:199], v[40:43]
	v_mfma_f32_16x16x32_bf16 v[32:35], v[180:183], v[196:199], v[32:35]
	v_mfma_f32_16x16x32_bf16 v[24:27], v[172:175], v[204:207], v[24:27]
	v_mfma_f32_16x16x32_bf16 v[16:19], v[180:183], v[204:207], v[16:19]
	v_mfma_f32_16x16x32_bf16 v[8:11], v[172:175], v[212:215], v[8:11]
	v_mfma_f32_16x16x32_bf16 v[0:3], v[180:183], v[212:215], v[0:3]
	s_barrier
	s_add_i32 s72, s72, 2
	s_add_u32 s30, s30, 0x100
	s_addc_u32 s31, s31, 0
	s_add_u32 s70, s70, 0x100
	s_addc_u32 s71, s71, 0
	s_cmp_gt_u32 s72, 29
	s_cbranch_scc0 .LBB0_167
	s_and_b64 vcc, exec, s[20:21]
	s_cbranch_vccz .LBB0_170
	s_barrier

.LBB0_360:
	v_add_u32_e32 v128, 0, v189
	v_add_u32_e32 v129, 0x10000, v128
	v_add_u32_e32 v140, 0x14000, v128
	ds_read_b128 v[144:147], v129
	ds_read_b128 v[148:151], v129 offset:1024
	ds_read_b128 v[152:155], v129 offset:2048
	ds_read_b128 v[156:159], v129 offset:3072
	ds_read_b128 v[128:131], v140
	ds_read_b128 v[132:135], v140 offset:1024
	ds_read_b128 v[136:139], v140 offset:2048
	ds_read_b128 v[140:143], v140 offset:3072
	s_cmpk_lg_i32 s63, 0x54
	s_cselect_b64 s[36:37], -1, 0
	s_add_u32 s34, s22, s30
	s_addc_u32 s35, s23, s31
	s_add_u32 s34, s34, s28
	s_addc_u32 s35, s35, s29
	v_lshl_add_u64 v[216:217], s[34:35], 0, v[160:161]
	v_lshl_add_u64 v[216:217], v[216:217], 0, s[18:19]
	s_add_i32 m0, s44, 0xc000
	v_mov_b32_e32 v173, v161
	ds_read_b128 v[176:179], v190
	ds_read_b128 v[180:183], v190 offset:1024
	ds_read_b128 v[192:195], v190 offset:2048
	ds_read_b128 v[196:199], v190 offset:3072
	ds_read_b128 v[200:203], v190 offset:4096
	ds_read_b128 v[204:207], v190 offset:5120
	ds_read_b128 v[208:211], v190 offset:6144
	ds_read_b128 v[212:215], v190 offset:7168
	global_load_lds_dwordx4 v[216:217], off
	v_lshl_add_u64 v[216:217], s[34:35], 0, v[172:173]
	v_lshl_add_u64 v[216:217], v[216:217], 0, s[18:19]
	s_add_i32 m0, s44, 0xe000
	s_nop 0
	global_load_lds_dwordx4 v[216:217], off
	s_waitcnt vmcnt(8)
	s_waitcnt lgkmcnt(0)
	s_barrier
	s_waitcnt lgkmcnt(0)
	v_mfma_f32_16x16x32_bf16 v[124:127], v[144:147], v[176:179], v[124:127]
	v_mfma_f32_16x16x32_bf16 v[120:123], v[152:155], v[176:179], v[120:123]
	v_mfma_f32_16x16x32_bf16 v[108:111], v[144:147], v[192:195], v[108:111]
	v_mfma_f32_16x16x32_bf16 v[104:107], v[152:155], v[192:195], v[104:107]
	v_mfma_f32_16x16x32_bf16 v[92:95], v[144:147], v[200:203], v[92:95]
	v_mfma_f32_16x16x32_bf16 v[88:91], v[152:155], v[200:203], v[88:91]
	v_mfma_f32_16x16x32_bf16 v[76:79], v[144:147], v[208:211], v[76:79]
	v_mfma_f32_16x16x32_bf16 v[72:75], v[152:155], v[208:211], v[72:75]
	v_mfma_f32_16x16x32_bf16 v[124:127], v[148:151], v[180:183], v[124:127]
	v_mfma_f32_16x16x32_bf16 v[120:123], v[156:159], v[180:183], v[120:123]
	v_mfma_f32_16x16x32_bf16 v[108:111], v[148:151], v[196:199], v[108:111]
	v_mfma_f32_16x16x32_bf16 v[104:107], v[156:159], v[196:199], v[104:107]
	v_mfma_f32_16x16x32_bf16 v[92:95], v[148:151], v[204:207], v[92:95]
	v_mfma_f32_16x16x32_bf16 v[88:91], v[156:159], v[204:207], v[88:91]
	v_mfma_f32_16x16x32_bf16 v[76:79], v[148:151], v[212:215], v[76:79]
	v_mfma_f32_16x16x32_bf16 v[72:75], v[156:159], v[212:215], v[72:75]
	v_mfma_f32_16x16x32_bf16 v[116:119], v[128:131], v[176:179], v[116:119]
	v_mfma_f32_16x16x32_bf16 v[112:115], v[136:139], v[176:179], v[112:115]
	v_mfma_f32_16x16x32_bf16 v[100:103], v[128:131], v[192:195], v[100:103]
	v_mfma_f32_16x16x32_bf16 v[96:99], v[136:139], v[192:195], v[96:99]
	v_mfma_f32_16x16x32_bf16 v[84:87], v[128:131], v[200:203], v[84:87]
	v_mfma_f32_16x16x32_bf16 v[80:83], v[136:139], v[200:203], v[80:83]
	v_mfma_f32_16x16x32_bf16 v[68:71], v[128:131], v[208:211], v[68:71]
	v_mfma_f32_16x16x32_bf16 v[64:67], v[136:139], v[208:211], v[64:67]
	v_mfma_f32_16x16x32_bf16 v[116:119], v[132:135], v[180:183], v[116:119]
	v_mfma_f32_16x16x32_bf16 v[112:115], v[140:143], v[180:183], v[112:115]
	v_mfma_f32_16x16x32_bf16 v[100:103], v[132:135], v[196:199], v[100:103]
	v_mfma_f32_16x16x32_bf16 v[96:99], v[140:143], v[196:199], v[96:99]
	v_mfma_f32_16x16x32_bf16 v[84:87], v[132:135], v[204:207], v[84:87]
	v_mfma_f32_16x16x32_bf16 v[80:83], v[140:143], v[204:207], v[80:83]
	v_mfma_f32_16x16x32_bf16 v[68:71], v[132:135], v[212:215], v[68:71]
	v_mfma_f32_16x16x32_bf16 v[64:67], v[140:143], v[212:215], v[64:67]
	s_barrier
	s_or_b64 s[84:85], s[8:9], s[36:37]
	s_mov_b64 s[34:35], 0x80000
	s_andn2_b64 vcc, exec, s[84:85]
	v_mov_b64_e32 v[180:181], v[164:165]
	v_mov_b64_e32 v[182:183], v[162:163]
	v_mov_b64_e32 v[176:177], v[164:165]
	v_mov_b64_e32 v[178:179], v[162:163]
	v_mov_b32_e32 v171, v164
	v_mov_b32_e32 v175, v162
	v_mov_b32_e32 v191, v164
	v_mov_b32_e32 v192, v162
	s_cbranch_vccnz .LBB0_362
	v_mov_b32_e32 v171, v161
	v_mov_b32_e32 v175, v161
	v_mov_b64_e32 v[180:181], v[174:175]
	v_mov_b64_e32 v[182:183], v[170:171]
	v_mov_b64_e32 v[176:177], v[172:173]
	v_mov_b64_e32 v[178:179], v[160:161]
	v_mov_b32_e32 v171, v172
	v_mov_b32_e32 v175, v160
	v_mov_b32_e32 v191, v174
	v_mov_b32_e32 v192, v170
	s_mov_b64 s[34:35], s[28:29]
.LBB0_362:
	s_add_u32 s28, s22, s30
	s_addc_u32 s29, s23, s31
	s_add_u32 s84, s28, 0x100
	s_addc_u32 s85, s29, 0
	s_and_b64 s[28:29], s[36:37], exec
	s_cselect_b32 s29, s85, s83
	s_cselect_b32 s28, s84, s96
	s_add_u32 s84, s80, s30
	s_addc_u32 s85, s81, s31
	s_and_b64 s[36:37], s[36:37], exec
	s_cselect_b32 s37, s85, s97
	s_cselect_b32 s36, s84, s62
	s_mov_b32 m0, s45
	v_lshl_add_u64 v[172:173], s[36:37], 0, v[182:183]
	v_lshl_add_u64 v[222:223], s[36:37], 0, v[180:181]
	s_add_u32 s36, s36, s34
	ds_read_b128 v[194:197], v190 offset:16384
	ds_read_b128 v[198:201], v190 offset:17408
	ds_read_b128 v[202:205], v190 offset:18432
	ds_read_b128 v[206:209], v190 offset:19456
	ds_read_b128 v[210:213], v190 offset:20480
	ds_read_b128 v[214:217], v190 offset:21504
	ds_read_b128 v[218:221], v190 offset:22528
	ds_read_b128 v[226:229], v190 offset:23552
	global_load_lds_dwordx4 v[172:173], off
	s_mov_b32 m0, s58
	s_addc_u32 s37, s37, s35
	global_load_lds_dwordx4 v[222:223], off
	v_lshl_add_u64 v[230:231], s[36:37], 0, v[182:183]
	s_mov_b32 m0, s59
	v_lshl_add_u64 v[232:233], s[36:37], 0, v[180:181]
	global_load_lds_dwordx4 v[230:231], off
	s_mov_b32 m0, s60
	v_lshl_add_u64 v[234:235], s[28:29], 0, v[178:179]
	global_load_lds_dwordx4 v[232:233], off
	s_mov_b32 m0, s44
	v_lshl_add_u64 v[236:237], s[28:29], 0, v[176:177]
	global_load_lds_dwordx4 v[234:235], off
	s_mov_b32 m0, s61
	s_nop 0
	global_load_lds_dwordx4 v[236:237], off
	s_waitcnt vmcnt(8)
	s_waitcnt lgkmcnt(0)
	s_barrier
	s_waitcnt lgkmcnt(0)
	v_mfma_f32_16x16x32_bf16 v[60:63], v[144:147], v[194:197], v[60:63]
	v_mfma_f32_16x16x32_bf16 v[56:59], v[152:155], v[194:197], v[56:59]
	v_mfma_f32_16x16x32_bf16 v[44:47], v[144:147], v[202:205], v[44:47]
	v_mfma_f32_16x16x32_bf16 v[40:43], v[152:155], v[202:205], v[40:43]
	v_mfma_f32_16x16x32_bf16 v[28:31], v[144:147], v[210:213], v[28:31]
	v_mfma_f32_16x16x32_bf16 v[24:27], v[152:155], v[210:213], v[24:27]
	v_mfma_f32_16x16x32_bf16 v[12:15], v[144:147], v[218:221], v[12:15]
	v_mfma_f32_16x16x32_bf16 v[8:11], v[152:155], v[218:221], v[8:11]
	v_mfma_f32_16x16x32_bf16 v[60:63], v[148:151], v[198:201], v[60:63]
	v_mfma_f32_16x16x32_bf16 v[56:59], v[156:159], v[198:201], v[56:59]
	v_mfma_f32_16x16x32_bf16 v[44:47], v[148:151], v[206:209], v[44:47]
	v_mfma_f32_16x16x32_bf16 v[40:43], v[156:159], v[206:209], v[40:43]
	v_mfma_f32_16x16x32_bf16 v[28:31], v[148:151], v[214:217], v[28:31]
	v_mfma_f32_16x16x32_bf16 v[24:27], v[156:159], v[214:217], v[24:27]
	v_mfma_f32_16x16x32_bf16 v[12:15], v[148:151], v[226:229], v[12:15]
	v_mfma_f32_16x16x32_bf16 v[8:11], v[156:159], v[226:229], v[8:11]
	v_mfma_f32_16x16x32_bf16 v[52:55], v[128:131], v[194:197], v[52:55]
	v_mfma_f32_16x16x32_bf16 v[48:51], v[136:139], v[194:197], v[48:51]
	v_mfma_f32_16x16x32_bf16 v[36:39], v[128:131], v[202:205], v[36:39]
	v_mfma_f32_16x16x32_bf16 v[32:35], v[136:139], v[202:205], v[32:35]
	v_mfma_f32_16x16x32_bf16 v[20:23], v[128:131], v[210:213], v[20:23]
	v_mfma_f32_16x16x32_bf16 v[16:19], v[136:139], v[210:213], v[16:19]
	v_mfma_f32_16x16x32_bf16 v[4:7], v[128:131], v[218:221], v[4:7]
	v_mfma_f32_16x16x32_bf16 v[0:3], v[136:139], v[218:221], v[0:3]
	v_mfma_f32_16x16x32_bf16 v[52:55], v[132:135], v[198:201], v[52:55]
	v_mfma_f32_16x16x32_bf16 v[48:51], v[140:143], v[198:201], v[48:51]
	v_mfma_f32_16x16x32_bf16 v[36:39], v[132:135], v[206:209], v[36:39]
	v_mfma_f32_16x16x32_bf16 v[32:35], v[140:143], v[206:209], v[32:35]
	v_mfma_f32_16x16x32_bf16 v[20:23], v[132:135], v[214:217], v[20:23]
	v_mfma_f32_16x16x32_bf16 v[16:19], v[140:143], v[214:217], v[16:19]
	v_mfma_f32_16x16x32_bf16 v[4:7], v[132:135], v[226:229], v[4:7]
	v_mfma_f32_16x16x32_bf16 v[0:3], v[140:143], v[226:229], v[0:3]
	s_barrier
	s_add_i32 s36, 0, 0x18000
	s_add_i32 s37, 0, 0x1c000
	v_add_u32_e32 v140, s36, v189
	v_add_u32_e32 v156, s37, v189
	ds_read_b128 v[128:131], v140
	ds_read_b128 v[132:135], v140 offset:1024
	ds_read_b128 v[136:139], v140 offset:2048
	ds_read_b128 v[140:143], v140 offset:3072
	ds_read_b128 v[144:147], v156
	ds_read_b128 v[148:151], v156 offset:1024
	ds_read_b128 v[152:155], v156 offset:2048
	ds_read_b128 v[156:159], v156 offset:3072
	s_add_u32 s28, s28, s34
	s_addc_u32 s29, s29, s35
	s_mov_b32 m0, s69
	v_lshl_add_u64 v[178:179], s[28:29], 0, v[178:179]
	ds_read_b128 v[180:183], v190 offset:32768
	ds_read_b128 v[194:197], v190 offset:33792
	ds_read_b128 v[198:201], v190 offset:34816
	ds_read_b128 v[202:205], v190 offset:35840
	ds_read_b128 v[206:209], v190 offset:36864
	ds_read_b128 v[210:213], v190 offset:37888
	ds_read_b128 v[214:217], v190 offset:38912
	ds_read_b128 v[218:221], v190 offset:39936
	global_load_lds_dwordx4 v[178:179], off
	v_lshl_add_u64 v[176:177], s[28:29], 0, v[176:177]
	s_mov_b32 m0, s72
	s_nop 0
	global_load_lds_dwordx4 v[176:177], off
	s_waitcnt vmcnt(8)
	s_waitcnt lgkmcnt(0)
	s_barrier
	s_waitcnt lgkmcnt(0)
	v_mfma_f32_16x16x32_bf16 v[124:127], v[128:131], v[180:183], v[124:127]
	v_mfma_f32_16x16x32_bf16 v[120:123], v[136:139], v[180:183], v[120:123]
	v_mfma_f32_16x16x32_bf16 v[108:111], v[128:131], v[198:201], v[108:111]
	v_mfma_f32_16x16x32_bf16 v[104:107], v[136:139], v[198:201], v[104:107]
	v_mfma_f32_16x16x32_bf16 v[92:95], v[128:131], v[206:209], v[92:95]
	v_mfma_f32_16x16x32_bf16 v[88:91], v[136:139], v[206:209], v[88:91]
	v_mfma_f32_16x16x32_bf16 v[76:79], v[128:131], v[214:217], v[76:79]
	v_mfma_f32_16x16x32_bf16 v[72:75], v[136:139], v[214:217], v[72:75]
	v_mfma_f32_16x16x32_bf16 v[124:127], v[132:135], v[194:197], v[124:127]
	v_mfma_f32_16x16x32_bf16 v[120:123], v[140:143], v[194:197], v[120:123]
	v_mfma_f32_16x16x32_bf16 v[108:111], v[132:135], v[202:205], v[108:111]
	v_mfma_f32_16x16x32_bf16 v[104:107], v[140:143], v[202:205], v[104:107]
	v_mfma_f32_16x16x32_bf16 v[92:95], v[132:135], v[210:213], v[92:95]
	v_mfma_f32_16x16x32_bf16 v[88:91], v[140:143], v[210:213], v[88:91]
	v_mfma_f32_16x16x32_bf16 v[76:79], v[132:135], v[218:221], v[76:79]
	v_mfma_f32_16x16x32_bf16 v[72:75], v[140:143], v[218:221], v[72:75]
	v_mfma_f32_16x16x32_bf16 v[116:119], v[144:147], v[180:183], v[116:119]
	v_mfma_f32_16x16x32_bf16 v[112:115], v[152:155], v[180:183], v[112:115]
	v_mfma_f32_16x16x32_bf16 v[100:103], v[144:147], v[198:201], v[100:103]
	v_mfma_f32_16x16x32_bf16 v[96:99], v[152:155], v[198:201], v[96:99]
	v_mfma_f32_16x16x32_bf16 v[84:87], v[144:147], v[206:209], v[84:87]
	v_mfma_f32_16x16x32_bf16 v[80:83], v[152:155], v[206:209], v[80:83]
	v_mfma_f32_16x16x32_bf16 v[68:71], v[144:147], v[214:217], v[68:71]
	v_mfma_f32_16x16x32_bf16 v[64:67], v[152:155], v[214:217], v[64:67]
	v_mfma_f32_16x16x32_bf16 v[116:119], v[148:151], v[194:197], v[116:119]
	v_mfma_f32_16x16x32_bf16 v[112:115], v[156:159], v[194:197], v[112:115]
	v_mfma_f32_16x16x32_bf16 v[100:103], v[148:151], v[202:205], v[100:103]
	v_mfma_f32_16x16x32_bf16 v[96:99], v[156:159], v[202:205], v[96:99]
	v_mfma_f32_16x16x32_bf16 v[84:87], v[148:151], v[210:213], v[84:87]
	v_mfma_f32_16x16x32_bf16 v[80:83], v[156:159], v[210:213], v[80:83]
	v_mfma_f32_16x16x32_bf16 v[68:71], v[148:151], v[218:221], v[68:71]
	v_mfma_f32_16x16x32_bf16 v[64:67], v[156:159], v[218:221], v[64:67]
	s_barrier
	s_add_i32 s28, s36, s3
	v_lshl_add_u64 v[172:173], v[172:173], 0, s[18:19]
	s_mov_b32 m0, s28
	ds_read_b128 v[176:179], v190 offset:49152
	ds_read_b128 v[180:183], v190 offset:50176
	ds_read_b128 v[194:197], v190 offset:51200
	ds_read_b128 v[198:201], v190 offset:52224
	ds_read_b128 v[202:205], v190 offset:53248
	ds_read_b128 v[206:209], v190 offset:54272
	ds_read_b128 v[210:213], v190 offset:55296
	ds_read_b128 v[214:217], v190 offset:56320
	global_load_lds_dwordx4 v[172:173], off
	v_lshl_add_u64 v[172:173], v[222:223], 0, s[18:19]
	s_add_i32 m0, s28, 0x2000
	s_add_i32 s28, s37, s3
	global_load_lds_dwordx4 v[172:173], off
	v_lshl_add_u64 v[172:173], v[230:231], 0, s[18:19]
	s_mov_b32 m0, s28
	s_nop 0
	global_load_lds_dwordx4 v[172:173], off
	v_lshl_add_u64 v[172:173], v[232:233], 0, s[18:19]
	s_add_i32 m0, s28, 0x2000
	s_nop 0
	global_load_lds_dwordx4 v[172:173], off
	v_lshl_add_u64 v[172:173], v[234:235], 0, s[18:19]
	s_mov_b32 m0, s74
	s_nop 0
	global_load_lds_dwordx4 v[172:173], off
	v_lshl_add_u64 v[172:173], v[236:237], 0, s[18:19]
	s_mov_b32 m0, s75
	s_nop 0
	global_load_lds_dwordx4 v[172:173], off
	s_waitcnt vmcnt(8)
	s_waitcnt lgkmcnt(0)
	s_barrier
	s_waitcnt lgkmcnt(0)
	v_mfma_f32_16x16x32_bf16 v[60:63], v[128:131], v[176:179], v[60:63]
	v_mfma_f32_16x16x32_bf16 v[56:59], v[136:139], v[176:179], v[56:59]
	v_mfma_f32_16x16x32_bf16 v[44:47], v[128:131], v[194:197], v[44:47]
	v_mfma_f32_16x16x32_bf16 v[40:43], v[136:139], v[194:197], v[40:43]
	v_mfma_f32_16x16x32_bf16 v[28:31], v[128:131], v[202:205], v[28:31]
	v_mfma_f32_16x16x32_bf16 v[24:27], v[136:139], v[202:205], v[24:27]
	v_mfma_f32_16x16x32_bf16 v[12:15], v[128:131], v[210:213], v[12:15]
	v_mfma_f32_16x16x32_bf16 v[8:11], v[136:139], v[210:213], v[8:11]
	v_mfma_f32_16x16x32_bf16 v[60:63], v[132:135], v[180:183], v[60:63]
	v_mfma_f32_16x16x32_bf16 v[56:59], v[140:143], v[180:183], v[56:59]
	v_mfma_f32_16x16x32_bf16 v[44:47], v[132:135], v[198:201], v[44:47]
	v_mfma_f32_16x16x32_bf16 v[40:43], v[140:143], v[198:201], v[40:43]
	v_mfma_f32_16x16x32_bf16 v[28:31], v[132:135], v[206:209], v[28:31]
	v_mfma_f32_16x16x32_bf16 v[24:27], v[140:143], v[206:209], v[24:27]
	v_mfma_f32_16x16x32_bf16 v[12:15], v[132:135], v[214:217], v[12:15]
	v_mfma_f32_16x16x32_bf16 v[8:11], v[140:143], v[214:217], v[8:11]
	v_mfma_f32_16x16x32_bf16 v[52:55], v[144:147], v[176:179], v[52:55]
	v_mfma_f32_16x16x32_bf16 v[48:51], v[152:155], v[176:179], v[48:51]
	v_mfma_f32_16x16x32_bf16 v[36:39], v[144:147], v[194:197], v[36:39]
	v_mfma_f32_16x16x32_bf16 v[32:35], v[152:155], v[194:197], v[32:35]
	v_mfma_f32_16x16x32_bf16 v[20:23], v[144:147], v[202:205], v[20:23]
	v_mfma_f32_16x16x32_bf16 v[16:19], v[152:155], v[202:205], v[16:19]
	v_mfma_f32_16x16x32_bf16 v[4:7], v[144:147], v[210:213], v[4:7]
	v_mfma_f32_16x16x32_bf16 v[0:3], v[152:155], v[210:213], v[0:3]
	v_mfma_f32_16x16x32_bf16 v[52:55], v[148:151], v[180:183], v[52:55]
	v_mfma_f32_16x16x32_bf16 v[48:51], v[156:159], v[180:183], v[48:51]
	v_mfma_f32_16x16x32_bf16 v[36:39], v[148:151], v[198:201], v[36:39]
	v_mfma_f32_16x16x32_bf16 v[32:35], v[156:159], v[198:201], v[32:35]
	v_mfma_f32_16x16x32_bf16 v[20:23], v[148:151], v[206:209], v[20:23]
	v_mfma_f32_16x16x32_bf16 v[16:19], v[156:159], v[206:209], v[16:19]
	v_mfma_f32_16x16x32_bf16 v[4:7], v[148:151], v[214:217], v[4:7]
	v_mfma_f32_16x16x32_bf16 v[0:3], v[156:159], v[214:217], v[0:3]
	s_barrier
	s_add_i32 s63, s63, 2
	s_add_u32 s30, s30, 0x100
	s_addc_u32 s31, s31, 0
	s_cmpk_gt_u32 s63, 0x55
	s_cbranch_scc1 .LBB0_364
	v_mov_b32_e32 v172, v171
	v_mov_b32_e32 v160, v175
	v_mov_b32_e32 v174, v191
	v_mov_b32_e32 v170, v192
	s_mov_b64 s[28:29], s[34:35]
	s_branch .LBB0_360

.LBB0_454:
	ds_read_b128 v[146:149], v160
	ds_read_b128 v[150:153], v160 offset:1024
	ds_read_b128 v[154:157], v160 offset:2048
	ds_read_b128 v[166:169], v160 offset:3072
	ds_read_b128 v[170:173], v161
	ds_read_b128 v[174:177], v161 offset:1024
	ds_read_b128 v[178:181], v161 offset:2048
	ds_read_b128 v[182:185], v161 offset:3072
	s_add_u32 s38, s36, 0xfff80080
	s_addc_u32 s39, s37, -1
	s_cmp_eq_u32 s63, 28
	s_cselect_b32 s41, s9, s39
	s_cselect_b32 s40, s10, s38
	s_cselect_b32 s39, s25, s62
	s_cselect_b32 s38, s27, s35
	v_lshl_add_u64 v[218:219], s[36:37], 0, v[138:139]
	s_add_i32 m0, s60, 0xc000
	ds_read_b128 v[186:189], v162
	ds_read_b128 v[190:193], v162 offset:1024
	ds_read_b128 v[194:197], v162 offset:2048
	ds_read_b128 v[198:201], v162 offset:3072
	ds_read_b128 v[202:205], v162 offset:4096
	ds_read_b128 v[206:209], v162 offset:5120
	ds_read_b128 v[210:213], v162 offset:6144
	ds_read_b128 v[214:217], v162 offset:7168
	global_load_lds_dwordx4 v[218:219], off
	v_lshl_add_u64 v[218:219], s[36:37], 0, v[140:141]
	s_add_i32 m0, s60, 0xe000
	s_nop 0
	global_load_lds_dwordx4 v[218:219], off
	s_waitcnt vmcnt(8)
	s_waitcnt lgkmcnt(0)
	s_barrier
	s_waitcnt lgkmcnt(0)
	v_mfma_f32_16x16x32_bf16 v[124:127], v[146:149], v[186:189], v[124:127]
	v_mfma_f32_16x16x32_bf16 v[120:123], v[154:157], v[186:189], v[120:123]
	v_mfma_f32_16x16x32_bf16 v[108:111], v[146:149], v[194:197], v[108:111]
	v_mfma_f32_16x16x32_bf16 v[104:107], v[154:157], v[194:197], v[104:107]
	v_mfma_f32_16x16x32_bf16 v[92:95], v[146:149], v[202:205], v[92:95]
	v_mfma_f32_16x16x32_bf16 v[88:91], v[154:157], v[202:205], v[88:91]
	v_mfma_f32_16x16x32_bf16 v[76:79], v[146:149], v[210:213], v[76:79]
	v_mfma_f32_16x16x32_bf16 v[72:75], v[154:157], v[210:213], v[72:75]
	v_mfma_f32_16x16x32_bf16 v[124:127], v[150:153], v[190:193], v[124:127]
	v_mfma_f32_16x16x32_bf16 v[120:123], v[166:169], v[190:193], v[120:123]
	v_mfma_f32_16x16x32_bf16 v[108:111], v[150:153], v[198:201], v[108:111]
	v_mfma_f32_16x16x32_bf16 v[104:107], v[166:169], v[198:201], v[104:107]
	v_mfma_f32_16x16x32_bf16 v[92:95], v[150:153], v[206:209], v[92:95]
	v_mfma_f32_16x16x32_bf16 v[88:91], v[166:169], v[206:209], v[88:91]
	v_mfma_f32_16x16x32_bf16 v[76:79], v[150:153], v[214:217], v[76:79]
	v_mfma_f32_16x16x32_bf16 v[72:75], v[166:169], v[214:217], v[72:75]
	v_mfma_f32_16x16x32_bf16 v[116:119], v[170:173], v[186:189], v[116:119]
	v_mfma_f32_16x16x32_bf16 v[112:115], v[178:181], v[186:189], v[112:115]
	v_mfma_f32_16x16x32_bf16 v[100:103], v[170:173], v[194:197], v[100:103]
	v_mfma_f32_16x16x32_bf16 v[96:99], v[178:181], v[194:197], v[96:99]
	v_mfma_f32_16x16x32_bf16 v[84:87], v[170:173], v[202:205], v[84:87]
	v_mfma_f32_16x16x32_bf16 v[80:83], v[178:181], v[202:205], v[80:83]
	v_mfma_f32_16x16x32_bf16 v[68:71], v[170:173], v[210:213], v[68:71]
	v_mfma_f32_16x16x32_bf16 v[64:67], v[178:181], v[210:213], v[64:67]
	v_mfma_f32_16x16x32_bf16 v[116:119], v[174:177], v[190:193], v[116:119]
	v_mfma_f32_16x16x32_bf16 v[112:115], v[182:185], v[190:193], v[112:115]
	v_mfma_f32_16x16x32_bf16 v[100:103], v[174:177], v[198:201], v[100:103]
	v_mfma_f32_16x16x32_bf16 v[96:99], v[182:185], v[198:201], v[96:99]
	v_mfma_f32_16x16x32_bf16 v[84:87], v[174:177], v[206:209], v[84:87]
	v_mfma_f32_16x16x32_bf16 v[80:83], v[182:185], v[206:209], v[80:83]
	v_mfma_f32_16x16x32_bf16 v[68:71], v[174:177], v[214:217], v[68:71]
	v_mfma_f32_16x16x32_bf16 v[64:67], v[182:185], v[214:217], v[64:67]
	s_barrier
	s_add_i32 s84, s78, s3
	v_lshl_add_u64 v[218:219], s[38:39], 0, v[130:131]
	s_mov_b32 m0, s84
	ds_read_b128 v[186:189], v162 offset:16384
	ds_read_b128 v[190:193], v162 offset:17408
	ds_read_b128 v[194:197], v162 offset:18432
	ds_read_b128 v[198:201], v162 offset:19456
	ds_read_b128 v[202:205], v162 offset:20480
	ds_read_b128 v[206:209], v162 offset:21504
	ds_read_b128 v[210:213], v162 offset:22528
	ds_read_b128 v[214:217], v162 offset:23552
	global_load_lds_dwordx4 v[218:219], off
	s_add_i32 m0, s84, 0x2000
	s_add_u32 s84, s38, 0x80000
	v_lshl_add_u64 v[220:221], s[38:39], 0, v[134:135]
	s_addc_u32 s85, s39, 0
	s_add_i32 s89, s79, s3
	global_load_lds_dwordx4 v[220:221], off
	v_lshl_add_u64 v[222:223], s[84:85], 0, v[130:131]
	s_mov_b32 m0, s89
	v_lshl_add_u64 v[226:227], s[40:41], 0, v[132:133]
	global_load_lds_dwordx4 v[222:223], off
	v_lshl_add_u64 v[222:223], s[84:85], 0, v[134:135]
	s_add_i32 m0, s89, 0x2000
	s_nop 0
	global_load_lds_dwordx4 v[222:223], off
	v_lshl_add_u64 v[222:223], s[40:41], 0, v[128:129]
	s_mov_b32 m0, s60
	s_nop 0
	global_load_lds_dwordx4 v[222:223], off
	s_mov_b32 m0, s61
	s_nop 0
	global_load_lds_dwordx4 v[226:227], off
	s_waitcnt vmcnt(8)
	s_waitcnt lgkmcnt(0)
	s_barrier
	s_waitcnt lgkmcnt(0)
	v_mfma_f32_16x16x32_bf16 v[60:63], v[146:149], v[186:189], v[60:63]
	v_mfma_f32_16x16x32_bf16 v[56:59], v[154:157], v[186:189], v[56:59]
	v_mfma_f32_16x16x32_bf16 v[44:47], v[146:149], v[194:197], v[44:47]
	v_mfma_f32_16x16x32_bf16 v[40:43], v[154:157], v[194:197], v[40:43]
	v_mfma_f32_16x16x32_bf16 v[28:31], v[146:149], v[202:205], v[28:31]
	v_mfma_f32_16x16x32_bf16 v[24:27], v[154:157], v[202:205], v[24:27]
	v_mfma_f32_16x16x32_bf16 v[12:15], v[146:149], v[210:213], v[12:15]
	v_mfma_f32_16x16x32_bf16 v[8:11], v[154:157], v[210:213], v[8:11]
	v_mfma_f32_16x16x32_bf16 v[60:63], v[150:153], v[190:193], v[60:63]
	v_mfma_f32_16x16x32_bf16 v[56:59], v[166:169], v[190:193], v[56:59]
	v_mfma_f32_16x16x32_bf16 v[44:47], v[150:153], v[198:201], v[44:47]
	v_mfma_f32_16x16x32_bf16 v[40:43], v[166:169], v[198:201], v[40:43]
	v_mfma_f32_16x16x32_bf16 v[28:31], v[150:153], v[206:209], v[28:31]
	v_mfma_f32_16x16x32_bf16 v[24:27], v[166:169], v[206:209], v[24:27]
	v_mfma_f32_16x16x32_bf16 v[12:15], v[150:153], v[214:217], v[12:15]
	v_mfma_f32_16x16x32_bf16 v[8:11], v[166:169], v[214:217], v[8:11]
	v_mfma_f32_16x16x32_bf16 v[52:55], v[170:173], v[186:189], v[52:55]
	v_mfma_f32_16x16x32_bf16 v[48:51], v[178:181], v[186:189], v[48:51]
	v_mfma_f32_16x16x32_bf16 v[36:39], v[170:173], v[194:197], v[36:39]
	v_mfma_f32_16x16x32_bf16 v[32:35], v[178:181], v[194:197], v[32:35]
	v_mfma_f32_16x16x32_bf16 v[20:23], v[170:173], v[202:205], v[20:23]
	v_mfma_f32_16x16x32_bf16 v[16:19], v[178:181], v[202:205], v[16:19]
	v_mfma_f32_16x16x32_bf16 v[4:7], v[170:173], v[210:213], v[4:7]
	v_mfma_f32_16x16x32_bf16 v[0:3], v[178:181], v[210:213], v[0:3]
	v_mfma_f32_16x16x32_bf16 v[52:55], v[174:177], v[190:193], v[52:55]
	v_mfma_f32_16x16x32_bf16 v[48:51], v[182:185], v[190:193], v[48:51]
	v_mfma_f32_16x16x32_bf16 v[36:39], v[174:177], v[198:201], v[36:39]
	v_mfma_f32_16x16x32_bf16 v[32:35], v[182:185], v[198:201], v[32:35]
	v_mfma_f32_16x16x32_bf16 v[20:23], v[174:177], v[206:209], v[20:23]
	v_mfma_f32_16x16x32_bf16 v[16:19], v[182:185], v[206:209], v[16:19]
	v_mfma_f32_16x16x32_bf16 v[4:7], v[174:177], v[214:217], v[4:7]
	v_mfma_f32_16x16x32_bf16 v[0:3], v[182:185], v[214:217], v[0:3]
	s_barrier
	s_add_i32 s84, 0, 0x18000
	v_add_u32_e32 v165, s84, v159
	s_add_i32 s85, 0, 0x1c000
	ds_read_b128 v[146:149], v165
	ds_read_b128 v[150:153], v165 offset:1024
	ds_read_b128 v[154:157], v165 offset:2048
	ds_read_b128 v[166:169], v165 offset:3072
	v_add_u32_e32 v165, s85, v159
	ds_read_b128 v[170:173], v165
	ds_read_b128 v[174:177], v165 offset:1024
	ds_read_b128 v[178:181], v165 offset:2048
	ds_read_b128 v[182:185], v165 offset:3072
	s_add_u32 s40, s40, 0x80000
	s_addc_u32 s41, s41, 0
	s_mov_b32 m0, s69
	v_lshl_add_u64 v[228:229], s[40:41], 0, v[128:129]
	ds_read_b128 v[186:189], v162 offset:32768
	ds_read_b128 v[190:193], v162 offset:33792
	ds_read_b128 v[194:197], v162 offset:34816
	ds_read_b128 v[198:201], v162 offset:35840
	ds_read_b128 v[202:205], v162 offset:36864
	ds_read_b128 v[206:209], v162 offset:37888
	ds_read_b128 v[210:213], v162 offset:38912
	ds_read_b128 v[214:217], v162 offset:39936
	global_load_lds_dwordx4 v[228:229], off
	v_lshl_add_u64 v[228:229], s[40:41], 0, v[132:133]
	s_mov_b32 m0, s72
	s_nop 0
	global_load_lds_dwordx4 v[228:229], off
	s_waitcnt vmcnt(8)
	s_waitcnt lgkmcnt(0)
	s_barrier
	s_waitcnt lgkmcnt(0)
	v_mfma_f32_16x16x32_bf16 v[124:127], v[146:149], v[186:189], v[124:127]
	v_mfma_f32_16x16x32_bf16 v[120:123], v[154:157], v[186:189], v[120:123]
	v_mfma_f32_16x16x32_bf16 v[108:111], v[146:149], v[194:197], v[108:111]
	v_mfma_f32_16x16x32_bf16 v[104:107], v[154:157], v[194:197], v[104:107]
	v_mfma_f32_16x16x32_bf16 v[92:95], v[146:149], v[202:205], v[92:95]
	v_mfma_f32_16x16x32_bf16 v[88:91], v[154:157], v[202:205], v[88:91]
	v_mfma_f32_16x16x32_bf16 v[76:79], v[146:149], v[210:213], v[76:79]
	v_mfma_f32_16x16x32_bf16 v[72:75], v[154:157], v[210:213], v[72:75]
	v_mfma_f32_16x16x32_bf16 v[124:127], v[150:153], v[190:193], v[124:127]
	v_mfma_f32_16x16x32_bf16 v[120:123], v[166:169], v[190:193], v[120:123]
	v_mfma_f32_16x16x32_bf16 v[108:111], v[150:153], v[198:201], v[108:111]
	v_mfma_f32_16x16x32_bf16 v[104:107], v[166:169], v[198:201], v[104:107]
	v_mfma_f32_16x16x32_bf16 v[92:95], v[150:153], v[206:209], v[92:95]
	v_mfma_f32_16x16x32_bf16 v[88:91], v[166:169], v[206:209], v[88:91]
	v_mfma_f32_16x16x32_bf16 v[76:79], v[150:153], v[214:217], v[76:79]
	v_mfma_f32_16x16x32_bf16 v[72:75], v[166:169], v[214:217], v[72:75]
	v_mfma_f32_16x16x32_bf16 v[116:119], v[170:173], v[186:189], v[116:119]
	v_mfma_f32_16x16x32_bf16 v[112:115], v[178:181], v[186:189], v[112:115]
	v_mfma_f32_16x16x32_bf16 v[100:103], v[170:173], v[194:197], v[100:103]
	v_mfma_f32_16x16x32_bf16 v[96:99], v[178:181], v[194:197], v[96:99]
	v_mfma_f32_16x16x32_bf16 v[84:87], v[170:173], v[202:205], v[84:87]
	v_mfma_f32_16x16x32_bf16 v[80:83], v[178:181], v[202:205], v[80:83]
	v_mfma_f32_16x16x32_bf16 v[68:71], v[170:173], v[210:213], v[68:71]
	v_mfma_f32_16x16x32_bf16 v[64:67], v[178:181], v[210:213], v[64:67]
	v_mfma_f32_16x16x32_bf16 v[116:119], v[174:177], v[190:193], v[116:119]
	v_mfma_f32_16x16x32_bf16 v[112:115], v[182:185], v[190:193], v[112:115]
	v_mfma_f32_16x16x32_bf16 v[100:103], v[174:177], v[198:201], v[100:103]
	v_mfma_f32_16x16x32_bf16 v[96:99], v[182:185], v[198:201], v[96:99]
	v_mfma_f32_16x16x32_bf16 v[84:87], v[174:177], v[206:209], v[84:87]
	v_mfma_f32_16x16x32_bf16 v[80:83], v[182:185], v[206:209], v[80:83]
	v_mfma_f32_16x16x32_bf16 v[68:71], v[174:177], v[214:217], v[68:71]
	v_mfma_f32_16x16x32_bf16 v[64:67], v[182:185], v[214:217], v[64:67]
	s_barrier
	s_add_i32 s40, s84, s3
	v_lshl_add_u64 v[218:219], v[218:219], 0, s[18:19]
	s_mov_b32 m0, s40
	ds_read_b128 v[186:189], v162 offset:49152
	ds_read_b128 v[190:193], v162 offset:50176
	ds_read_b128 v[194:197], v162 offset:51200
	ds_read_b128 v[198:201], v162 offset:52224
	ds_read_b128 v[202:205], v162 offset:53248
	ds_read_b128 v[206:209], v162 offset:54272
	ds_read_b128 v[210:213], v162 offset:55296
	ds_read_b128 v[214:217], v162 offset:56320
	global_load_lds_dwordx4 v[218:219], off
	s_add_i32 m0, s40, 0x2000
	s_add_u32 s38, s38, 0x80080
	v_lshl_add_u64 v[218:219], v[220:221], 0, s[18:19]
	s_addc_u32 s39, s39, 0
	s_add_i32 s40, s85, s3
	global_load_lds_dwordx4 v[218:219], off
	v_lshl_add_u64 v[218:219], s[38:39], 0, v[130:131]
	s_mov_b32 m0, s40
	s_nop 0
	global_load_lds_dwordx4 v[218:219], off
	v_lshl_add_u64 v[218:219], s[38:39], 0, v[134:135]
	s_add_i32 m0, s40, 0x2000
	s_nop 0
	global_load_lds_dwordx4 v[218:219], off
	v_lshl_add_u64 v[218:219], v[222:223], 0, s[18:19]
	s_mov_b32 m0, s73
	s_nop 0
	global_load_lds_dwordx4 v[218:219], off
	v_lshl_add_u64 v[218:219], v[226:227], 0, s[18:19]
	s_mov_b32 m0, s74
	s_nop 0
	global_load_lds_dwordx4 v[218:219], off
	s_waitcnt vmcnt(8)
	s_waitcnt lgkmcnt(0)
	s_barrier
	s_waitcnt lgkmcnt(0)
	v_mfma_f32_16x16x32_bf16 v[60:63], v[146:149], v[186:189], v[60:63]
	v_mfma_f32_16x16x32_bf16 v[56:59], v[154:157], v[186:189], v[56:59]
	v_mfma_f32_16x16x32_bf16 v[44:47], v[146:149], v[194:197], v[44:47]
	v_mfma_f32_16x16x32_bf16 v[40:43], v[154:157], v[194:197], v[40:43]
	v_mfma_f32_16x16x32_bf16 v[28:31], v[146:149], v[202:205], v[28:31]
	v_mfma_f32_16x16x32_bf16 v[24:27], v[154:157], v[202:205], v[24:27]
	v_mfma_f32_16x16x32_bf16 v[12:15], v[146:149], v[210:213], v[12:15]
	v_mfma_f32_16x16x32_bf16 v[8:11], v[154:157], v[210:213], v[8:11]
	v_mfma_f32_16x16x32_bf16 v[60:63], v[150:153], v[190:193], v[60:63]
	v_mfma_f32_16x16x32_bf16 v[56:59], v[166:169], v[190:193], v[56:59]
	v_mfma_f32_16x16x32_bf16 v[44:47], v[150:153], v[198:201], v[44:47]
	v_mfma_f32_16x16x32_bf16 v[40:43], v[166:169], v[198:201], v[40:43]
	v_mfma_f32_16x16x32_bf16 v[28:31], v[150:153], v[206:209], v[28:31]
	v_mfma_f32_16x16x32_bf16 v[24:27], v[166:169], v[206:209], v[24:27]
	v_mfma_f32_16x16x32_bf16 v[12:15], v[150:153], v[214:217], v[12:15]
	v_mfma_f32_16x16x32_bf16 v[8:11], v[166:169], v[214:217], v[8:11]
	v_mfma_f32_16x16x32_bf16 v[52:55], v[170:173], v[186:189], v[52:55]
	v_mfma_f32_16x16x32_bf16 v[48:51], v[178:181], v[186:189], v[48:51]
	v_mfma_f32_16x16x32_bf16 v[36:39], v[170:173], v[194:197], v[36:39]
	v_mfma_f32_16x16x32_bf16 v[32:35], v[178:181], v[194:197], v[32:35]
	v_mfma_f32_16x16x32_bf16 v[20:23], v[170:173], v[202:205], v[20:23]
	v_mfma_f32_16x16x32_bf16 v[16:19], v[178:181], v[202:205], v[16:19]
	v_mfma_f32_16x16x32_bf16 v[4:7], v[170:173], v[210:213], v[4:7]
	v_mfma_f32_16x16x32_bf16 v[0:3], v[178:181], v[210:213], v[0:3]
	v_mfma_f32_16x16x32_bf16 v[52:55], v[174:177], v[190:193], v[52:55]
	v_mfma_f32_16x16x32_bf16 v[48:51], v[182:185], v[190:193], v[48:51]
	v_mfma_f32_16x16x32_bf16 v[36:39], v[174:177], v[198:201], v[36:39]
	v_mfma_f32_16x16x32_bf16 v[32:35], v[182:185], v[198:201], v[32:35]
	v_mfma_f32_16x16x32_bf16 v[20:23], v[174:177], v[206:209], v[20:23]
	v_mfma_f32_16x16x32_bf16 v[16:19], v[182:185], v[206:209], v[16:19]
	v_mfma_f32_16x16x32_bf16 v[4:7], v[174:177], v[214:217], v[4:7]
	v_mfma_f32_16x16x32_bf16 v[0:3], v[182:185], v[214:217], v[0:3]
	s_barrier
	s_add_i32 s63, s63, 2
	s_add_u32 s36, s36, 0x100
	s_addc_u32 s37, s37, 0
	s_add_u32 s35, s35, 0x100
	s_addc_u32 s62, s62, 0
	s_cmp_gt_u32 s63, 29
	s_cbranch_scc0 .LBB0_454
	s_and_b64 vcc, exec, s[20:21]
	s_cbranch_vccz .LBB0_457
	s_barrier

.LBB0_542:
	ds_read_b128 v[128:131], v167
	ds_read_b128 v[148:151], v167 offset:1024
	ds_read_b128 v[152:155], v167 offset:2048
	ds_read_b128 v[156:159], v167 offset:3072
	ds_read_b128 v[160:163], v168
	ds_read_b128 v[170:173], v168 offset:1024
	ds_read_b128 v[174:177], v168 offset:2048
	ds_read_b128 v[178:181], v168 offset:3072
	s_add_u32 s36, s8, 0xfff80080
	s_addc_u32 s37, s9, -1
	s_cmp_eq_u32 s81, 28
	s_cselect_b32 s39, s27, s37
	s_cselect_b32 s38, s62, s36
	s_cselect_b32 s37, s25, s80
	s_cselect_b32 s36, s63, s79
	v_lshl_add_u64 v[214:215], s[8:9], 0, v[140:141]
	s_add_i32 m0, s35, 0xc000
	ds_read_b128 v[182:185], v169
	ds_read_b128 v[186:189], v169 offset:1024
	ds_read_b128 v[190:193], v169 offset:2048
	ds_read_b128 v[194:197], v169 offset:3072
	ds_read_b128 v[198:201], v169 offset:4096
	ds_read_b128 v[202:205], v169 offset:5120
	ds_read_b128 v[206:209], v169 offset:6144
	ds_read_b128 v[210:213], v169 offset:7168
	global_load_lds_dwordx4 v[214:215], off
	v_lshl_add_u64 v[214:215], s[8:9], 0, v[142:143]
	s_add_i32 m0, s35, 0xe000
	s_nop 0
	global_load_lds_dwordx4 v[214:215], off
	s_waitcnt vmcnt(8)
	s_waitcnt lgkmcnt(0)
	s_barrier
	s_waitcnt lgkmcnt(0)
	v_mfma_f32_16x16x32_bf16 v[124:127], v[128:131], v[182:185], v[124:127]
	v_mfma_f32_16x16x32_bf16 v[120:123], v[152:155], v[182:185], v[120:123]
	v_mfma_f32_16x16x32_bf16 v[112:115], v[128:131], v[190:193], v[112:115]
	v_mfma_f32_16x16x32_bf16 v[104:107], v[152:155], v[190:193], v[104:107]
	v_mfma_f32_16x16x32_bf16 v[96:99], v[128:131], v[198:201], v[96:99]
	v_mfma_f32_16x16x32_bf16 v[88:91], v[152:155], v[198:201], v[88:91]
	v_mfma_f32_16x16x32_bf16 v[80:83], v[128:131], v[206:209], v[80:83]
	v_mfma_f32_16x16x32_bf16 v[72:75], v[152:155], v[206:209], v[72:75]
	v_mfma_f32_16x16x32_bf16 v[124:127], v[148:151], v[186:189], v[124:127]
	v_mfma_f32_16x16x32_bf16 v[120:123], v[156:159], v[186:189], v[120:123]
	v_mfma_f32_16x16x32_bf16 v[112:115], v[148:151], v[194:197], v[112:115]
	v_mfma_f32_16x16x32_bf16 v[104:107], v[156:159], v[194:197], v[104:107]
	v_mfma_f32_16x16x32_bf16 v[96:99], v[148:151], v[202:205], v[96:99]
	v_mfma_f32_16x16x32_bf16 v[88:91], v[156:159], v[202:205], v[88:91]
	v_mfma_f32_16x16x32_bf16 v[80:83], v[148:151], v[210:213], v[80:83]
	v_mfma_f32_16x16x32_bf16 v[72:75], v[156:159], v[210:213], v[72:75]
	v_mfma_f32_16x16x32_bf16 v[116:119], v[160:163], v[182:185], v[116:119]
	v_mfma_f32_16x16x32_bf16 v[108:111], v[174:177], v[182:185], v[108:111]
	v_mfma_f32_16x16x32_bf16 v[100:103], v[160:163], v[190:193], v[100:103]
	v_mfma_f32_16x16x32_bf16 v[92:95], v[174:177], v[190:193], v[92:95]
	v_mfma_f32_16x16x32_bf16 v[84:87], v[160:163], v[198:201], v[84:87]
	v_mfma_f32_16x16x32_bf16 v[76:79], v[174:177], v[198:201], v[76:79]
	v_mfma_f32_16x16x32_bf16 v[68:71], v[160:163], v[206:209], v[68:71]
	v_mfma_f32_16x16x32_bf16 v[64:67], v[174:177], v[206:209], v[64:67]
	v_mfma_f32_16x16x32_bf16 v[116:119], v[170:173], v[186:189], v[116:119]
	v_mfma_f32_16x16x32_bf16 v[108:111], v[178:181], v[186:189], v[108:111]
	v_mfma_f32_16x16x32_bf16 v[100:103], v[170:173], v[194:197], v[100:103]
	v_mfma_f32_16x16x32_bf16 v[92:95], v[178:181], v[194:197], v[92:95]
	v_mfma_f32_16x16x32_bf16 v[84:87], v[170:173], v[202:205], v[84:87]
	v_mfma_f32_16x16x32_bf16 v[76:79], v[178:181], v[202:205], v[76:79]
	v_mfma_f32_16x16x32_bf16 v[68:71], v[170:173], v[210:213], v[68:71]
	v_mfma_f32_16x16x32_bf16 v[64:67], v[178:181], v[210:213], v[64:67]
	s_barrier
	s_add_i32 s83, s75, s3
	v_lshl_add_u64 v[214:215], s[36:37], 0, v[134:135]
	s_mov_b32 m0, s83
	ds_read_b128 v[182:185], v169 offset:16384
	ds_read_b128 v[186:189], v169 offset:17408
	ds_read_b128 v[190:193], v169 offset:18432
	ds_read_b128 v[194:197], v169 offset:19456
	ds_read_b128 v[198:201], v169 offset:20480
	ds_read_b128 v[202:205], v169 offset:21504
	ds_read_b128 v[206:209], v169 offset:22528
	ds_read_b128 v[210:213], v169 offset:23552
	global_load_lds_dwordx4 v[214:215], off
	s_add_i32 m0, s83, 0x2000
	s_add_u32 s84, s36, 0x80000
	v_lshl_add_u64 v[216:217], s[36:37], 0, v[138:139]
	s_addc_u32 s85, s37, 0
	s_add_i32 s83, s76, s3
	global_load_lds_dwordx4 v[216:217], off
	v_lshl_add_u64 v[218:219], s[84:85], 0, v[134:135]
	s_mov_b32 m0, s83
	v_lshl_add_u64 v[220:221], s[38:39], 0, v[136:137]
	global_load_lds_dwordx4 v[218:219], off
	v_lshl_add_u64 v[218:219], s[84:85], 0, v[138:139]
	s_add_i32 m0, s83, 0x2000
	s_nop 0
	global_load_lds_dwordx4 v[218:219], off
	v_lshl_add_u64 v[218:219], s[38:39], 0, v[132:133]
	s_mov_b32 m0, s35
	s_nop 0
	global_load_lds_dwordx4 v[218:219], off
	s_mov_b32 m0, s41
	s_nop 0
	global_load_lds_dwordx4 v[220:221], off
	s_waitcnt vmcnt(8)
	s_waitcnt lgkmcnt(0)
	s_barrier
	s_waitcnt lgkmcnt(0)
	v_mfma_f32_16x16x32_bf16 v[60:63], v[128:131], v[182:185], v[60:63]
	v_mfma_f32_16x16x32_bf16 v[56:59], v[152:155], v[182:185], v[56:59]
	v_mfma_f32_16x16x32_bf16 v[48:51], v[128:131], v[190:193], v[48:51]
	v_mfma_f32_16x16x32_bf16 v[40:43], v[152:155], v[190:193], v[40:43]
	v_mfma_f32_16x16x32_bf16 v[32:35], v[128:131], v[198:201], v[32:35]
	v_mfma_f32_16x16x32_bf16 v[24:27], v[152:155], v[198:201], v[24:27]
	v_mfma_f32_16x16x32_bf16 v[16:19], v[128:131], v[206:209], v[16:19]
	v_mfma_f32_16x16x32_bf16 v[8:11], v[152:155], v[206:209], v[8:11]
	v_mfma_f32_16x16x32_bf16 v[60:63], v[148:151], v[186:189], v[60:63]
	v_mfma_f32_16x16x32_bf16 v[56:59], v[156:159], v[186:189], v[56:59]
	v_mfma_f32_16x16x32_bf16 v[48:51], v[148:151], v[194:197], v[48:51]
	v_mfma_f32_16x16x32_bf16 v[40:43], v[156:159], v[194:197], v[40:43]
	v_mfma_f32_16x16x32_bf16 v[32:35], v[148:151], v[202:205], v[32:35]
	v_mfma_f32_16x16x32_bf16 v[24:27], v[156:159], v[202:205], v[24:27]
	v_mfma_f32_16x16x32_bf16 v[16:19], v[148:151], v[210:213], v[16:19]
	v_mfma_f32_16x16x32_bf16 v[8:11], v[156:159], v[210:213], v[8:11]
	v_mfma_f32_16x16x32_bf16 v[52:55], v[160:163], v[182:185], v[52:55]
	v_mfma_f32_16x16x32_bf16 v[44:47], v[174:177], v[182:185], v[44:47]
	v_mfma_f32_16x16x32_bf16 v[36:39], v[160:163], v[190:193], v[36:39]
	v_mfma_f32_16x16x32_bf16 v[28:31], v[174:177], v[190:193], v[28:31]
	v_mfma_f32_16x16x32_bf16 v[20:23], v[160:163], v[198:201], v[20:23]
	v_mfma_f32_16x16x32_bf16 v[12:15], v[174:177], v[198:201], v[12:15]
	v_mfma_f32_16x16x32_bf16 v[4:7], v[160:163], v[206:209], v[4:7]
	v_mfma_f32_16x16x32_bf16 v[0:3], v[174:177], v[206:209], v[0:3]
	v_mfma_f32_16x16x32_bf16 v[52:55], v[170:173], v[186:189], v[52:55]
	v_mfma_f32_16x16x32_bf16 v[44:47], v[178:181], v[186:189], v[44:47]
	v_mfma_f32_16x16x32_bf16 v[36:39], v[170:173], v[194:197], v[36:39]
	v_mfma_f32_16x16x32_bf16 v[28:31], v[178:181], v[194:197], v[28:31]
	v_mfma_f32_16x16x32_bf16 v[20:23], v[170:173], v[202:205], v[20:23]
	v_mfma_f32_16x16x32_bf16 v[12:15], v[178:181], v[202:205], v[12:15]
	v_mfma_f32_16x16x32_bf16 v[4:7], v[170:173], v[210:213], v[4:7]
	v_mfma_f32_16x16x32_bf16 v[0:3], v[178:181], v[210:213], v[0:3]
	s_barrier
	s_add_i32 s83, 0, 0x18000
	s_add_i32 s84, 0, 0x1c000
	v_add_u32_e32 v156, s83, v165
	v_add_u32_e32 v178, s84, v165
	ds_read_b128 v[128:131], v156
	ds_read_b128 v[148:151], v156 offset:1024
	ds_read_b128 v[152:155], v156 offset:2048
	ds_read_b128 v[156:159], v156 offset:3072
	ds_read_b128 v[160:163], v178
	ds_read_b128 v[170:173], v178 offset:1024
	ds_read_b128 v[174:177], v178 offset:2048
	ds_read_b128 v[178:181], v178 offset:3072
	s_add_u32 s38, s38, 0x80000
	s_addc_u32 s39, s39, 0
	s_mov_b32 m0, s44
	v_lshl_add_u64 v[222:223], s[38:39], 0, v[132:133]
	ds_read_b128 v[182:185], v169 offset:32768
	ds_read_b128 v[186:189], v169 offset:33792
	ds_read_b128 v[190:193], v169 offset:34816
	ds_read_b128 v[194:197], v169 offset:35840
	ds_read_b128 v[198:201], v169 offset:36864
	ds_read_b128 v[202:205], v169 offset:37888
	ds_read_b128 v[206:209], v169 offset:38912
	ds_read_b128 v[210:213], v169 offset:39936
	global_load_lds_dwordx4 v[222:223], off
	v_lshl_add_u64 v[222:223], s[38:39], 0, v[136:137]
	s_mov_b32 m0, s45
	s_nop 0
	global_load_lds_dwordx4 v[222:223], off
	s_waitcnt vmcnt(8)
	s_waitcnt lgkmcnt(0)
	s_barrier
	s_waitcnt lgkmcnt(0)
	v_mfma_f32_16x16x32_bf16 v[124:127], v[128:131], v[182:185], v[124:127]
	v_mfma_f32_16x16x32_bf16 v[120:123], v[152:155], v[182:185], v[120:123]
	v_mfma_f32_16x16x32_bf16 v[112:115], v[128:131], v[190:193], v[112:115]
	v_mfma_f32_16x16x32_bf16 v[104:107], v[152:155], v[190:193], v[104:107]
	v_mfma_f32_16x16x32_bf16 v[96:99], v[128:131], v[198:201], v[96:99]
	v_mfma_f32_16x16x32_bf16 v[88:91], v[152:155], v[198:201], v[88:91]
	v_mfma_f32_16x16x32_bf16 v[80:83], v[128:131], v[206:209], v[80:83]
	v_mfma_f32_16x16x32_bf16 v[72:75], v[152:155], v[206:209], v[72:75]
	v_mfma_f32_16x16x32_bf16 v[124:127], v[148:151], v[186:189], v[124:127]
	v_mfma_f32_16x16x32_bf16 v[120:123], v[156:159], v[186:189], v[120:123]
	v_mfma_f32_16x16x32_bf16 v[112:115], v[148:151], v[194:197], v[112:115]
	v_mfma_f32_16x16x32_bf16 v[104:107], v[156:159], v[194:197], v[104:107]
	v_mfma_f32_16x16x32_bf16 v[96:99], v[148:151], v[202:205], v[96:99]
	v_mfma_f32_16x16x32_bf16 v[88:91], v[156:159], v[202:205], v[88:91]
	v_mfma_f32_16x16x32_bf16 v[80:83], v[148:151], v[210:213], v[80:83]
	v_mfma_f32_16x16x32_bf16 v[72:75], v[156:159], v[210:213], v[72:75]
	v_mfma_f32_16x16x32_bf16 v[116:119], v[160:163], v[182:185], v[116:119]
	v_mfma_f32_16x16x32_bf16 v[108:111], v[174:177], v[182:185], v[108:111]
	v_mfma_f32_16x16x32_bf16 v[100:103], v[160:163], v[190:193], v[100:103]
	v_mfma_f32_16x16x32_bf16 v[92:95], v[174:177], v[190:193], v[92:95]
	v_mfma_f32_16x16x32_bf16 v[84:87], v[160:163], v[198:201], v[84:87]
	v_mfma_f32_16x16x32_bf16 v[76:79], v[174:177], v[198:201], v[76:79]
	v_mfma_f32_16x16x32_bf16 v[68:71], v[160:163], v[206:209], v[68:71]
	v_mfma_f32_16x16x32_bf16 v[64:67], v[174:177], v[206:209], v[64:67]
	v_mfma_f32_16x16x32_bf16 v[116:119], v[170:173], v[186:189], v[116:119]
	v_mfma_f32_16x16x32_bf16 v[108:111], v[178:181], v[186:189], v[108:111]
	v_mfma_f32_16x16x32_bf16 v[100:103], v[170:173], v[194:197], v[100:103]
	v_mfma_f32_16x16x32_bf16 v[92:95], v[178:181], v[194:197], v[92:95]
	v_mfma_f32_16x16x32_bf16 v[84:87], v[170:173], v[202:205], v[84:87]
	v_mfma_f32_16x16x32_bf16 v[76:79], v[178:181], v[202:205], v[76:79]
	v_mfma_f32_16x16x32_bf16 v[68:71], v[170:173], v[210:213], v[68:71]
	v_mfma_f32_16x16x32_bf16 v[64:67], v[178:181], v[210:213], v[64:67]
	s_barrier
	s_add_i32 s38, s83, s3
	v_lshl_add_u64 v[214:215], v[214:215], 0, s[16:17]
	s_mov_b32 m0, s38
	ds_read_b128 v[182:185], v169 offset:49152
	ds_read_b128 v[186:189], v169 offset:50176
	ds_read_b128 v[190:193], v169 offset:51200
	ds_read_b128 v[194:197], v169 offset:52224
	ds_read_b128 v[198:201], v169 offset:53248
	ds_read_b128 v[202:205], v169 offset:54272
	ds_read_b128 v[206:209], v169 offset:55296
	ds_read_b128 v[210:213], v169 offset:56320
	global_load_lds_dwordx4 v[214:215], off
	s_add_i32 m0, s38, 0x2000
	s_add_u32 s36, s36, 0x80080
	v_lshl_add_u64 v[214:215], v[216:217], 0, s[16:17]
	s_addc_u32 s37, s37, 0
	s_add_i32 s38, s84, s3
	global_load_lds_dwordx4 v[214:215], off
	v_lshl_add_u64 v[214:215], s[36:37], 0, v[134:135]
	s_mov_b32 m0, s38
	s_nop 0
	global_load_lds_dwordx4 v[214:215], off
	v_lshl_add_u64 v[214:215], s[36:37], 0, v[138:139]
	s_add_i32 m0, s38, 0x2000
	s_nop 0
	global_load_lds_dwordx4 v[214:215], off
	v_lshl_add_u64 v[214:215], v[218:219], 0, s[16:17]
	s_mov_b32 m0, s61
	s_nop 0
	global_load_lds_dwordx4 v[214:215], off
	v_lshl_add_u64 v[214:215], v[220:221], 0, s[16:17]
	s_mov_b32 m0, s67
	s_nop 0
	global_load_lds_dwordx4 v[214:215], off
	s_waitcnt vmcnt(8)
	s_waitcnt lgkmcnt(0)
	s_barrier
	s_waitcnt lgkmcnt(0)
	v_mfma_f32_16x16x32_bf16 v[60:63], v[128:131], v[182:185], v[60:63]
	v_mfma_f32_16x16x32_bf16 v[56:59], v[152:155], v[182:185], v[56:59]
	v_mfma_f32_16x16x32_bf16 v[48:51], v[128:131], v[190:193], v[48:51]
	v_mfma_f32_16x16x32_bf16 v[40:43], v[152:155], v[190:193], v[40:43]
	v_mfma_f32_16x16x32_bf16 v[32:35], v[128:131], v[198:201], v[32:35]
	v_mfma_f32_16x16x32_bf16 v[24:27], v[152:155], v[198:201], v[24:27]
	v_mfma_f32_16x16x32_bf16 v[16:19], v[128:131], v[206:209], v[16:19]
	v_mfma_f32_16x16x32_bf16 v[8:11], v[152:155], v[206:209], v[8:11]
	v_mfma_f32_16x16x32_bf16 v[60:63], v[148:151], v[186:189], v[60:63]
	v_mfma_f32_16x16x32_bf16 v[56:59], v[156:159], v[186:189], v[56:59]
	v_mfma_f32_16x16x32_bf16 v[48:51], v[148:151], v[194:197], v[48:51]
	v_mfma_f32_16x16x32_bf16 v[40:43], v[156:159], v[194:197], v[40:43]
	v_mfma_f32_16x16x32_bf16 v[32:35], v[148:151], v[202:205], v[32:35]
	v_mfma_f32_16x16x32_bf16 v[24:27], v[156:159], v[202:205], v[24:27]
	v_mfma_f32_16x16x32_bf16 v[16:19], v[148:151], v[210:213], v[16:19]
	v_mfma_f32_16x16x32_bf16 v[8:11], v[156:159], v[210:213], v[8:11]
	v_mfma_f32_16x16x32_bf16 v[52:55], v[160:163], v[182:185], v[52:55]
	v_mfma_f32_16x16x32_bf16 v[44:47], v[174:177], v[182:185], v[44:47]
	v_mfma_f32_16x16x32_bf16 v[36:39], v[160:163], v[190:193], v[36:39]
	v_mfma_f32_16x16x32_bf16 v[28:31], v[174:177], v[190:193], v[28:31]
	v_mfma_f32_16x16x32_bf16 v[20:23], v[160:163], v[198:201], v[20:23]
	v_mfma_f32_16x16x32_bf16 v[12:15], v[174:177], v[198:201], v[12:15]
	v_mfma_f32_16x16x32_bf16 v[4:7], v[160:163], v[206:209], v[4:7]
	v_mfma_f32_16x16x32_bf16 v[0:3], v[174:177], v[206:209], v[0:3]
	v_mfma_f32_16x16x32_bf16 v[52:55], v[170:173], v[186:189], v[52:55]
	v_mfma_f32_16x16x32_bf16 v[44:47], v[178:181], v[186:189], v[44:47]
	v_mfma_f32_16x16x32_bf16 v[36:39], v[170:173], v[194:197], v[36:39]
	v_mfma_f32_16x16x32_bf16 v[28:31], v[178:181], v[194:197], v[28:31]
	v_mfma_f32_16x16x32_bf16 v[20:23], v[170:173], v[202:205], v[20:23]
	v_mfma_f32_16x16x32_bf16 v[12:15], v[178:181], v[202:205], v[12:15]
	v_mfma_f32_16x16x32_bf16 v[4:7], v[170:173], v[210:213], v[4:7]
	v_mfma_f32_16x16x32_bf16 v[0:3], v[178:181], v[210:213], v[0:3]
	s_barrier
	s_add_i32 s81, s81, 2
	s_add_u32 s8, s8, 0x100
	s_addc_u32 s9, s9, 0
	s_add_u32 s79, s79, 0x100
	s_addc_u32 s80, s80, 0
	s_cmp_gt_u32 s81, 29
	s_cbranch_scc0 .LBB0_542
	s_and_b64 vcc, exec, s[18:19]
	s_cbranch_vccz .LBB0_545
	s_barrier

.LBB0_948:
	v_add_u32_e32 v104, 0, v194
	v_add_u32_e32 v105, 0x10000, v104
	v_add_u32_e32 v104, 0x14000, v104
	ds_read_b128 v[152:155], v105
	ds_read_b128 v[156:159], v105 offset:1024
	ds_read_b128 v[160:163], v105 offset:2048
	ds_read_b128 v[164:167], v105 offset:3072
	ds_read_b128 v[136:139], v104
	ds_read_b128 v[140:143], v104 offset:1024
	ds_read_b128 v[144:147], v104 offset:2048
	ds_read_b128 v[148:151], v104 offset:3072
	s_cmp_lg_u32 s79, 28
	s_cselect_b64 s[38:39], -1, 0
	s_add_u32 s40, s34, s36
	s_addc_u32 s41, s35, s37
	v_lshl_add_u64 v[104:105], s[40:41], 0, v[168:169]
	v_lshl_add_u64 v[104:105], v[104:105], 0, s[20:21]
	s_add_i32 m0, s15, 0xc000
	v_mov_b32_e32 v181, v169
	ds_read_b128 v[184:187], v195
	ds_read_b128 v[196:199], v195 offset:1024
	ds_read_b128 v[200:203], v195 offset:2048
	ds_read_b128 v[204:207], v195 offset:3072
	ds_read_b128 v[208:211], v195 offset:4096
	ds_read_b128 v[212:215], v195 offset:5120
	ds_read_b128 v[216:219], v195 offset:6144
	ds_read_b128 v[220:223], v195 offset:7168
	global_load_lds_dwordx4 v[104:105], off
	v_lshl_add_u64 v[104:105], s[40:41], 0, v[180:181]
	v_lshl_add_u64 v[104:105], v[104:105], 0, s[20:21]
	s_add_i32 m0, s15, 0xe000
	s_nop 0
	global_load_lds_dwordx4 v[104:105], off
	s_waitcnt vmcnt(8)
	s_waitcnt lgkmcnt(0)
	s_barrier
	s_waitcnt lgkmcnt(0)
	v_mfma_f32_16x16x32_bf16 v[104:107], v[152:155], v[184:187], v[132:135]
	v_mfma_f32_16x16x32_bf16 v[124:127], v[160:163], v[184:187], v[128:131]
	v_mfma_f32_16x16x32_bf16 v[112:115], v[152:155], v[200:203], v[112:115]
	v_mfma_f32_16x16x32_bf16 v[108:111], v[160:163], v[200:203], v[108:111]
	v_mfma_f32_16x16x32_bf16 v[92:95], v[152:155], v[208:211], v[92:95]
	v_mfma_f32_16x16x32_bf16 v[88:91], v[160:163], v[208:211], v[88:91]
	v_mfma_f32_16x16x32_bf16 v[76:79], v[152:155], v[216:219], v[76:79]
	v_mfma_f32_16x16x32_bf16 v[72:75], v[160:163], v[216:219], v[72:75]
	v_mfma_f32_16x16x32_bf16 v[104:107], v[156:159], v[196:199], v[104:107]
	v_mfma_f32_16x16x32_bf16 v[124:127], v[164:167], v[196:199], v[124:127]
	v_mfma_f32_16x16x32_bf16 v[112:115], v[156:159], v[204:207], v[112:115]
	v_mfma_f32_16x16x32_bf16 v[108:111], v[164:167], v[204:207], v[108:111]
	v_mfma_f32_16x16x32_bf16 v[92:95], v[156:159], v[212:215], v[92:95]
	v_mfma_f32_16x16x32_bf16 v[88:91], v[164:167], v[212:215], v[88:91]
	v_mfma_f32_16x16x32_bf16 v[76:79], v[156:159], v[220:223], v[76:79]
	v_mfma_f32_16x16x32_bf16 v[72:75], v[164:167], v[220:223], v[72:75]
	v_mfma_f32_16x16x32_bf16 v[120:123], v[136:139], v[184:187], v[120:123]
	v_mfma_f32_16x16x32_bf16 v[116:119], v[144:147], v[184:187], v[116:119]
	v_mfma_f32_16x16x32_bf16 v[100:103], v[136:139], v[200:203], v[100:103]
	v_mfma_f32_16x16x32_bf16 v[96:99], v[144:147], v[200:203], v[96:99]
	v_mfma_f32_16x16x32_bf16 v[84:87], v[136:139], v[208:211], v[84:87]
	v_mfma_f32_16x16x32_bf16 v[80:83], v[144:147], v[208:211], v[80:83]
	v_mfma_f32_16x16x32_bf16 v[68:71], v[136:139], v[216:219], v[68:71]
	v_mfma_f32_16x16x32_bf16 v[64:67], v[144:147], v[216:219], v[64:67]
	v_mfma_f32_16x16x32_bf16 v[120:123], v[140:143], v[196:199], v[120:123]
	v_mfma_f32_16x16x32_bf16 v[116:119], v[148:151], v[196:199], v[116:119]
	v_mfma_f32_16x16x32_bf16 v[100:103], v[140:143], v[204:207], v[100:103]
	v_mfma_f32_16x16x32_bf16 v[96:99], v[148:151], v[204:207], v[96:99]
	v_mfma_f32_16x16x32_bf16 v[84:87], v[140:143], v[212:215], v[84:87]
	v_mfma_f32_16x16x32_bf16 v[80:83], v[148:151], v[212:215], v[80:83]
	v_mfma_f32_16x16x32_bf16 v[68:71], v[140:143], v[220:223], v[68:71]
	v_mfma_f32_16x16x32_bf16 v[64:67], v[148:151], v[220:223], v[64:67]
	s_barrier
	s_or_b64 s[40:41], s[8:9], s[38:39]
	s_andn2_b64 vcc, exec, s[40:41]
	v_mov_b64_e32 v[184:185], v[172:173]
	v_mov_b64_e32 v[186:187], v[170:171]
	v_mov_b64_e32 v[128:129], v[172:173]
	v_mov_b64_e32 v[130:131], v[170:171]
	v_mov_b32_e32 v179, v172
	v_mov_b32_e32 v183, v170
	v_mov_b32_e32 v196, v172
	v_mov_b32_e32 v197, v170
	s_cbranch_vccnz .LBB0_950
	v_mov_b32_e32 v179, v169
	v_mov_b32_e32 v183, v169
	v_mov_b64_e32 v[184:185], v[182:183]
	v_mov_b64_e32 v[186:187], v[178:179]
	v_mov_b64_e32 v[128:129], v[180:181]
	v_mov_b64_e32 v[130:131], v[168:169]
	v_mov_b32_e32 v179, v180
	v_mov_b32_e32 v183, v168
	v_mov_b32_e32 v196, v182
	v_mov_b32_e32 v197, v178
.LBB0_950:
	s_add_u32 s40, s34, s36
	s_addc_u32 s41, s35, s37
	s_add_u32 s80, s40, 0x100
	s_addc_u32 s81, s41, 0
	s_and_b64 s[40:41], s[38:39], exec
	s_cselect_b32 s41, s81, s27
	s_cselect_b32 s40, s80, s29
	s_add_u32 s80, s63, s36
	s_addc_u32 s81, s76, s37
	s_and_b64 s[38:39], s[38:39], exec
	s_cselect_b32 s39, s81, s77
	s_cselect_b32 s38, s80, s78
	s_mov_b32 m0, s61
	v_lshl_add_u64 v[180:181], s[38:39], 0, v[186:187]
	s_add_u32 s80, s38, 0x80000
	ds_read_b128 v[132:135], v195 offset:16384
	ds_read_b128 v[198:201], v195 offset:17408
	ds_read_b128 v[202:205], v195 offset:18432
	ds_read_b128 v[206:209], v195 offset:19456
	ds_read_b128 v[210:213], v195 offset:20480
	ds_read_b128 v[214:217], v195 offset:21504
	ds_read_b128 v[218:221], v195 offset:22528
	ds_read_b128 v[226:229], v195 offset:23552
	global_load_lds_dwordx4 v[180:181], off
	v_lshl_add_u64 v[222:223], s[38:39], 0, v[184:185]
	s_mov_b32 m0, s64
	s_addc_u32 s81, s39, 0
	global_load_lds_dwordx4 v[222:223], off
	v_lshl_add_u64 v[230:231], s[80:81], 0, v[186:187]
	s_mov_b32 m0, s65
	v_lshl_add_u64 v[234:235], s[40:41], 0, v[130:131]
	global_load_lds_dwordx4 v[230:231], off
	v_lshl_add_u64 v[230:231], s[80:81], 0, v[184:185]
	s_mov_b32 m0, s66
	v_lshl_add_u64 v[236:237], s[40:41], 0, v[128:129]
	global_load_lds_dwordx4 v[230:231], off
	s_mov_b32 m0, s15
	s_nop 0
	global_load_lds_dwordx4 v[234:235], off
	s_mov_b32 m0, s67
	s_nop 0
	global_load_lds_dwordx4 v[236:237], off
	s_waitcnt vmcnt(8)
	s_waitcnt lgkmcnt(0)
	s_barrier
	s_waitcnt lgkmcnt(0)
	v_mfma_f32_16x16x32_bf16 v[60:63], v[152:155], v[132:135], v[60:63]
	v_mfma_f32_16x16x32_bf16 v[56:59], v[160:163], v[132:135], v[56:59]
	v_mfma_f32_16x16x32_bf16 v[44:47], v[152:155], v[202:205], v[44:47]
	v_mfma_f32_16x16x32_bf16 v[40:43], v[160:163], v[202:205], v[40:43]
	v_mfma_f32_16x16x32_bf16 v[28:31], v[152:155], v[210:213], v[28:31]
	v_mfma_f32_16x16x32_bf16 v[24:27], v[160:163], v[210:213], v[24:27]
	v_mfma_f32_16x16x32_bf16 v[12:15], v[152:155], v[218:221], v[12:15]
	v_mfma_f32_16x16x32_bf16 v[8:11], v[160:163], v[218:221], v[8:11]
	v_mfma_f32_16x16x32_bf16 v[60:63], v[156:159], v[198:201], v[60:63]
	v_mfma_f32_16x16x32_bf16 v[56:59], v[164:167], v[198:201], v[56:59]
	v_mfma_f32_16x16x32_bf16 v[44:47], v[156:159], v[206:209], v[44:47]
	v_mfma_f32_16x16x32_bf16 v[40:43], v[164:167], v[206:209], v[40:43]
	v_mfma_f32_16x16x32_bf16 v[28:31], v[156:159], v[214:217], v[28:31]
	v_mfma_f32_16x16x32_bf16 v[24:27], v[164:167], v[214:217], v[24:27]
	v_mfma_f32_16x16x32_bf16 v[12:15], v[156:159], v[226:229], v[12:15]
	v_mfma_f32_16x16x32_bf16 v[8:11], v[164:167], v[226:229], v[8:11]
	v_mfma_f32_16x16x32_bf16 v[52:55], v[136:139], v[132:135], v[52:55]
	v_mfma_f32_16x16x32_bf16 v[48:51], v[144:147], v[132:135], v[48:51]
	v_mfma_f32_16x16x32_bf16 v[36:39], v[136:139], v[202:205], v[36:39]
	v_mfma_f32_16x16x32_bf16 v[32:35], v[144:147], v[202:205], v[32:35]
	v_mfma_f32_16x16x32_bf16 v[20:23], v[136:139], v[210:213], v[20:23]
	v_mfma_f32_16x16x32_bf16 v[16:19], v[144:147], v[210:213], v[16:19]
	v_mfma_f32_16x16x32_bf16 v[4:7], v[136:139], v[218:221], v[4:7]
	v_mfma_f32_16x16x32_bf16 v[0:3], v[144:147], v[218:221], v[0:3]
	v_mfma_f32_16x16x32_bf16 v[52:55], v[140:143], v[198:201], v[52:55]
	v_mfma_f32_16x16x32_bf16 v[48:51], v[148:151], v[198:201], v[48:51]
	v_mfma_f32_16x16x32_bf16 v[36:39], v[140:143], v[206:209], v[36:39]
	v_mfma_f32_16x16x32_bf16 v[32:35], v[148:151], v[206:209], v[32:35]
	v_mfma_f32_16x16x32_bf16 v[20:23], v[140:143], v[214:217], v[20:23]
	v_mfma_f32_16x16x32_bf16 v[16:19], v[148:151], v[214:217], v[16:19]
	v_mfma_f32_16x16x32_bf16 v[4:7], v[140:143], v[226:229], v[4:7]
	v_mfma_f32_16x16x32_bf16 v[0:3], v[148:151], v[226:229], v[0:3]
	s_barrier
	s_add_i32 s80, 0, 0x18000
	v_add_u32_e32 v132, s80, v194
	s_add_i32 s81, 0, 0x1c000
	ds_read_b128 v[136:139], v132
	ds_read_b128 v[140:143], v132 offset:1024
	ds_read_b128 v[144:147], v132 offset:2048
	ds_read_b128 v[148:151], v132 offset:3072
	v_add_u32_e32 v132, s81, v194
	ds_read_b128 v[152:155], v132
	ds_read_b128 v[156:159], v132 offset:1024
	ds_read_b128 v[160:163], v132 offset:2048
	ds_read_b128 v[164:167], v132 offset:3072
	s_add_u32 s40, s40, 0x80000
	s_addc_u32 s41, s41, 0
	s_mov_b32 m0, s68
	v_lshl_add_u64 v[130:131], s[40:41], 0, v[130:131]
	ds_read_b128 v[198:201], v195 offset:32768
	ds_read_b128 v[202:205], v195 offset:33792
	ds_read_b128 v[206:209], v195 offset:34816
	ds_read_b128 v[210:213], v195 offset:35840
	ds_read_b128 v[214:217], v195 offset:36864
	ds_read_b128 v[218:221], v195 offset:37888
	ds_read_b128 v[226:229], v195 offset:38912
	ds_read_b128 v[230:233], v195 offset:39936
	global_load_lds_dwordx4 v[130:131], off
	v_lshl_add_u64 v[128:129], s[40:41], 0, v[128:129]
	s_mov_b32 m0, s69
	s_nop 0
	global_load_lds_dwordx4 v[128:129], off
	s_waitcnt vmcnt(8)
	s_waitcnt lgkmcnt(0)
	s_barrier
	s_waitcnt lgkmcnt(0)
	v_mfma_f32_16x16x32_bf16 v[104:107], v[136:139], v[198:201], v[104:107]
	v_mfma_f32_16x16x32_bf16 v[132:135], v[140:143], v[202:205], v[104:107]
	v_mfma_f32_16x16x32_bf16 v[104:107], v[144:147], v[198:201], v[124:127]
	v_mfma_f32_16x16x32_bf16 v[128:131], v[148:151], v[202:205], v[104:107]
	v_mfma_f32_16x16x32_bf16 v[104:107], v[136:139], v[206:209], v[112:115]
	v_mfma_f32_16x16x32_bf16 v[112:115], v[140:143], v[210:213], v[104:107]
	v_mfma_f32_16x16x32_bf16 v[104:107], v[144:147], v[206:209], v[108:111]
	v_mfma_f32_16x16x32_bf16 v[92:95], v[136:139], v[214:217], v[92:95]
	v_mfma_f32_16x16x32_bf16 v[88:91], v[144:147], v[214:217], v[88:91]
	v_mfma_f32_16x16x32_bf16 v[76:79], v[136:139], v[226:229], v[76:79]
	v_mfma_f32_16x16x32_bf16 v[72:75], v[144:147], v[226:229], v[72:75]
	v_mfma_f32_16x16x32_bf16 v[108:111], v[148:151], v[210:213], v[104:107]
	v_mfma_f32_16x16x32_bf16 v[92:95], v[140:143], v[218:221], v[92:95]
	v_mfma_f32_16x16x32_bf16 v[88:91], v[148:151], v[218:221], v[88:91]
	v_mfma_f32_16x16x32_bf16 v[76:79], v[140:143], v[230:233], v[76:79]
	v_mfma_f32_16x16x32_bf16 v[72:75], v[148:151], v[230:233], v[72:75]
	v_mfma_f32_16x16x32_bf16 v[104:107], v[152:155], v[198:201], v[120:123]
	v_mfma_f32_16x16x32_bf16 v[120:123], v[156:159], v[202:205], v[104:107]
	v_mfma_f32_16x16x32_bf16 v[104:107], v[160:163], v[198:201], v[116:119]
	v_mfma_f32_16x16x32_bf16 v[100:103], v[152:155], v[206:209], v[100:103]
	v_mfma_f32_16x16x32_bf16 v[96:99], v[160:163], v[206:209], v[96:99]
	v_mfma_f32_16x16x32_bf16 v[84:87], v[152:155], v[214:217], v[84:87]
	v_mfma_f32_16x16x32_bf16 v[80:83], v[160:163], v[214:217], v[80:83]
	v_mfma_f32_16x16x32_bf16 v[68:71], v[152:155], v[226:229], v[68:71]
	v_mfma_f32_16x16x32_bf16 v[64:67], v[160:163], v[226:229], v[64:67]
	v_mfma_f32_16x16x32_bf16 v[116:119], v[164:167], v[202:205], v[104:107]
	v_mfma_f32_16x16x32_bf16 v[100:103], v[156:159], v[210:213], v[100:103]
	v_mfma_f32_16x16x32_bf16 v[96:99], v[164:167], v[210:213], v[96:99]
	v_mfma_f32_16x16x32_bf16 v[84:87], v[156:159], v[218:221], v[84:87]
	v_mfma_f32_16x16x32_bf16 v[80:83], v[164:167], v[218:221], v[80:83]
	v_mfma_f32_16x16x32_bf16 v[68:71], v[156:159], v[230:233], v[68:71]
	v_mfma_f32_16x16x32_bf16 v[64:67], v[164:167], v[230:233], v[64:67]
	s_barrier
	s_add_i32 s40, s80, s3
	v_lshl_add_u64 v[180:181], v[180:181], 0, s[18:19]
	s_mov_b32 m0, s40
	ds_read_b128 v[104:107], v195 offset:49152
	ds_read_b128 v[124:127], v195 offset:50176
	ds_read_b128 v[198:201], v195 offset:51200
	ds_read_b128 v[202:205], v195 offset:52224
	ds_read_b128 v[206:209], v195 offset:53248
	ds_read_b128 v[210:213], v195 offset:54272
	ds_read_b128 v[214:217], v195 offset:55296
	ds_read_b128 v[218:221], v195 offset:56320
	global_load_lds_dwordx4 v[180:181], off
	s_add_i32 m0, s40, 0x2000
	s_add_u32 s38, s38, 0x80080
	v_lshl_add_u64 v[180:181], v[222:223], 0, s[18:19]
	s_addc_u32 s39, s39, 0
	s_add_i32 s40, s81, s3
	global_load_lds_dwordx4 v[180:181], off
	v_lshl_add_u64 v[180:181], s[38:39], 0, v[186:187]
	s_mov_b32 m0, s40
	s_nop 0
	global_load_lds_dwordx4 v[180:181], off
	v_lshl_add_u64 v[180:181], s[38:39], 0, v[184:185]
	s_add_i32 m0, s40, 0x2000
	s_nop 0
	global_load_lds_dwordx4 v[180:181], off
	v_lshl_add_u64 v[180:181], v[234:235], 0, s[18:19]
	s_mov_b32 m0, s70
	s_nop 0
	global_load_lds_dwordx4 v[180:181], off
	v_lshl_add_u64 v[180:181], v[236:237], 0, s[18:19]
	s_mov_b32 m0, s71
	s_nop 0
	global_load_lds_dwordx4 v[180:181], off
	s_waitcnt vmcnt(8)
	s_waitcnt lgkmcnt(0)
	s_barrier
	s_waitcnt lgkmcnt(0)
	v_mfma_f32_16x16x32_bf16 v[60:63], v[136:139], v[104:107], v[60:63]
	v_mfma_f32_16x16x32_bf16 v[56:59], v[144:147], v[104:107], v[56:59]
	v_mfma_f32_16x16x32_bf16 v[44:47], v[136:139], v[198:201], v[44:47]
	v_mfma_f32_16x16x32_bf16 v[40:43], v[144:147], v[198:201], v[40:43]
	v_mfma_f32_16x16x32_bf16 v[28:31], v[136:139], v[206:209], v[28:31]
	v_mfma_f32_16x16x32_bf16 v[24:27], v[144:147], v[206:209], v[24:27]
	v_mfma_f32_16x16x32_bf16 v[12:15], v[136:139], v[214:217], v[12:15]
	v_mfma_f32_16x16x32_bf16 v[8:11], v[144:147], v[214:217], v[8:11]
	v_mfma_f32_16x16x32_bf16 v[60:63], v[140:143], v[124:127], v[60:63]
	v_mfma_f32_16x16x32_bf16 v[56:59], v[148:151], v[124:127], v[56:59]
	v_mfma_f32_16x16x32_bf16 v[44:47], v[140:143], v[202:205], v[44:47]
	v_mfma_f32_16x16x32_bf16 v[40:43], v[148:151], v[202:205], v[40:43]
	v_mfma_f32_16x16x32_bf16 v[28:31], v[140:143], v[210:213], v[28:31]
	v_mfma_f32_16x16x32_bf16 v[24:27], v[148:151], v[210:213], v[24:27]
	v_mfma_f32_16x16x32_bf16 v[12:15], v[140:143], v[218:221], v[12:15]
	v_mfma_f32_16x16x32_bf16 v[8:11], v[148:151], v[218:221], v[8:11]
	v_mfma_f32_16x16x32_bf16 v[52:55], v[152:155], v[104:107], v[52:55]
	v_mfma_f32_16x16x32_bf16 v[48:51], v[160:163], v[104:107], v[48:51]
	v_mfma_f32_16x16x32_bf16 v[36:39], v[152:155], v[198:201], v[36:39]
	v_mfma_f32_16x16x32_bf16 v[32:35], v[160:163], v[198:201], v[32:35]
	v_mfma_f32_16x16x32_bf16 v[20:23], v[152:155], v[206:209], v[20:23]
	v_mfma_f32_16x16x32_bf16 v[16:19], v[160:163], v[206:209], v[16:19]
	v_mfma_f32_16x16x32_bf16 v[4:7], v[152:155], v[214:217], v[4:7]
	v_mfma_f32_16x16x32_bf16 v[0:3], v[160:163], v[214:217], v[0:3]
	v_mfma_f32_16x16x32_bf16 v[52:55], v[156:159], v[124:127], v[52:55]
	v_mfma_f32_16x16x32_bf16 v[48:51], v[164:167], v[124:127], v[48:51]
	v_mfma_f32_16x16x32_bf16 v[36:39], v[156:159], v[202:205], v[36:39]
	v_mfma_f32_16x16x32_bf16 v[32:35], v[164:167], v[202:205], v[32:35]
	v_mfma_f32_16x16x32_bf16 v[20:23], v[156:159], v[210:213], v[20:23]
	v_mfma_f32_16x16x32_bf16 v[16:19], v[164:167], v[210:213], v[16:19]
	v_mfma_f32_16x16x32_bf16 v[4:7], v[156:159], v[218:221], v[4:7]
	v_mfma_f32_16x16x32_bf16 v[0:3], v[164:167], v[218:221], v[0:3]
	s_barrier
	s_add_i32 s79, s79, 2
	s_add_u32 s36, s36, 0x100
	s_addc_u32 s37, s37, 0
	s_cmp_gt_u32 s79, 29
	s_cbranch_scc1 .LBB0_952
	v_mov_b32_e32 v180, v179
	v_mov_b32_e32 v168, v183
	v_mov_b32_e32 v182, v196
	v_mov_b32_e32 v178, v197
	s_branch .LBB0_948

.LBB0_997:
	s_add_u32 s27, s30, s38
	s_addc_u32 s39, s31, 0
	s_add_u32 s44, s27, 0x100
	s_addc_u32 s45, s39, 0
	s_and_b64 s[40:41], s[36:37], exec
	s_cselect_b32 s41, s21, s45
	s_cselect_b32 s40, s62, s44
	s_add_u32 s38, s28, s38
	s_addc_u32 s44, s29, 0
	s_add_u32 s38, s38, 0x100
	s_addc_u32 s44, s44, 0
	s_and_b64 s[36:37], s[36:37], exec
	s_cselect_b32 s45, s19, s44
	s_cselect_b32 s44, s63, s38
	s_add_u32 s66, s27, 0x10080
	ds_read_b128 v[146:149], v143
	ds_read_b128 v[150:153], v143 offset:1024
	ds_read_b128 v[154:157], v143 offset:2048
	ds_read_b128 v[158:161], v143 offset:3072
	ds_read_b128 v[162:165], v144
	ds_read_b128 v[166:169], v144 offset:1024
	ds_read_b128 v[170:173], v144 offset:2048
	ds_read_b128 v[174:177], v144 offset:3072
	s_addc_u32 s67, s39, 0
	s_add_i32 s89, s79, s3
	s_add_i32 m0, s90, 0xc000
	s_add_i32 s27, s90, 0xe000
	s_add_i32 s84, s89, 0x2000
	s_add_u32 s64, s44, 0x10000
	s_addc_u32 s65, s45, 0
	s_add_i32 s85, s80, s3
	s_add_i32 s93, s85, 0x2000
	s_add_i32 vcc_lo, 0, 0x18000
	s_add_i32 vcc_hi, 0, 0x1c000
	s_add_u32 s38, s40, 0x10000
	s_addc_u32 s39, s41, 0
	s_add_i32 s96, vcc_lo, s3
	s_add_i32 s95, s96, 0x2000
	s_add_u32 s36, s44, 0x10080
	s_addc_u32 s37, s45, 0
	s_add_i32 s97, vcc_hi, s3
	s_add_i32 s83, s97, 0x2000
	v_lshl_add_u64 v[210:211], s[66:67], 0, v[128:129]
	ds_read_b128 v[178:181], v145
	ds_read_b128 v[182:185], v145 offset:1024
	ds_read_b128 v[186:189], v145 offset:2048
	ds_read_b128 v[190:193], v145 offset:3072
	ds_read_b128 v[194:197], v145 offset:4096
	ds_read_b128 v[198:201], v145 offset:5120
	ds_read_b128 v[202:205], v145 offset:6144
	ds_read_b128 v[206:209], v145 offset:7168
	global_load_lds_dwordx4 v[210:211], off
	v_lshl_add_u64 v[210:211], s[66:67], 0, v[132:133]
	s_mov_b32 m0, s27
	s_nop 0
	global_load_lds_dwordx4 v[210:211], off
	s_waitcnt vmcnt(8)
	s_waitcnt lgkmcnt(0)
	s_barrier
	s_waitcnt lgkmcnt(0)
	v_mfma_f32_16x16x32_bf16 v[124:127], v[146:149], v[178:181], v[124:127]
	v_mfma_f32_16x16x32_bf16 v[120:123], v[154:157], v[178:181], v[120:123]
	v_mfma_f32_16x16x32_bf16 v[116:119], v[146:149], v[186:189], v[116:119]
	v_mfma_f32_16x16x32_bf16 v[108:111], v[154:157], v[186:189], v[108:111]
	v_mfma_f32_16x16x32_bf16 v[100:103], v[146:149], v[194:197], v[100:103]
	v_mfma_f32_16x16x32_bf16 v[92:95], v[154:157], v[194:197], v[92:95]
	v_mfma_f32_16x16x32_bf16 v[84:87], v[146:149], v[202:205], v[84:87]
	v_mfma_f32_16x16x32_bf16 v[76:79], v[154:157], v[202:205], v[76:79]
	v_mfma_f32_16x16x32_bf16 v[124:127], v[150:153], v[182:185], v[124:127]
	v_mfma_f32_16x16x32_bf16 v[120:123], v[158:161], v[182:185], v[120:123]
	v_mfma_f32_16x16x32_bf16 v[116:119], v[150:153], v[190:193], v[116:119]
	v_mfma_f32_16x16x32_bf16 v[108:111], v[158:161], v[190:193], v[108:111]
	v_mfma_f32_16x16x32_bf16 v[100:103], v[150:153], v[198:201], v[100:103]
	v_mfma_f32_16x16x32_bf16 v[92:95], v[158:161], v[198:201], v[92:95]
	v_mfma_f32_16x16x32_bf16 v[84:87], v[150:153], v[206:209], v[84:87]
	v_mfma_f32_16x16x32_bf16 v[76:79], v[158:161], v[206:209], v[76:79]
	v_mfma_f32_16x16x32_bf16 v[112:115], v[162:165], v[178:181], v[112:115]
	v_mfma_f32_16x16x32_bf16 v[104:107], v[170:173], v[178:181], v[104:107]
	v_mfma_f32_16x16x32_bf16 v[96:99], v[162:165], v[186:189], v[96:99]
	v_mfma_f32_16x16x32_bf16 v[88:91], v[170:173], v[186:189], v[88:91]
	v_mfma_f32_16x16x32_bf16 v[80:83], v[162:165], v[194:197], v[80:83]
	v_mfma_f32_16x16x32_bf16 v[72:75], v[170:173], v[194:197], v[72:75]
	v_mfma_f32_16x16x32_bf16 v[68:71], v[162:165], v[202:205], v[68:71]
	v_mfma_f32_16x16x32_bf16 v[64:67], v[170:173], v[202:205], v[64:67]
	v_mfma_f32_16x16x32_bf16 v[112:115], v[166:169], v[182:185], v[112:115]
	v_mfma_f32_16x16x32_bf16 v[104:107], v[174:177], v[182:185], v[104:107]
	v_mfma_f32_16x16x32_bf16 v[96:99], v[166:169], v[190:193], v[96:99]
	v_mfma_f32_16x16x32_bf16 v[88:91], v[174:177], v[190:193], v[88:91]
	v_mfma_f32_16x16x32_bf16 v[80:83], v[166:169], v[198:201], v[80:83]
	v_mfma_f32_16x16x32_bf16 v[72:75], v[174:177], v[198:201], v[72:75]
	v_mfma_f32_16x16x32_bf16 v[68:71], v[166:169], v[206:209], v[68:71]
	v_mfma_f32_16x16x32_bf16 v[64:67], v[174:177], v[206:209], v[64:67]
	s_barrier
	s_mov_b32 m0, s89
	v_lshl_add_u64 v[210:211], s[44:45], 0, v[130:131]
	ds_read_b128 v[178:181], v145 offset:16384
	ds_read_b128 v[182:185], v145 offset:17408
	ds_read_b128 v[186:189], v145 offset:18432
	ds_read_b128 v[190:193], v145 offset:19456
	ds_read_b128 v[194:197], v145 offset:20480
	ds_read_b128 v[198:201], v145 offset:21504
	ds_read_b128 v[202:205], v145 offset:22528
	ds_read_b128 v[206:209], v145 offset:23552
	global_load_lds_dwordx4 v[210:211], off
	v_lshl_add_u64 v[212:213], s[44:45], 0, v[134:135]
	s_mov_b32 m0, s84
	v_lshl_add_u64 v[214:215], s[64:65], 0, v[130:131]
	global_load_lds_dwordx4 v[212:213], off
	s_mov_b32 m0, s85
	v_lshl_add_u64 v[216:217], s[40:41], 0, v[132:133]
	global_load_lds_dwordx4 v[214:215], off
	v_lshl_add_u64 v[214:215], s[64:65], 0, v[134:135]
	s_mov_b32 m0, s93
	s_nop 0
	global_load_lds_dwordx4 v[214:215], off
	v_lshl_add_u64 v[214:215], s[40:41], 0, v[128:129]
	s_mov_b32 m0, s90
	s_nop 0
	global_load_lds_dwordx4 v[214:215], off
	s_mov_b32 m0, s71
	s_nop 0
	global_load_lds_dwordx4 v[216:217], off
	s_waitcnt vmcnt(8)
	s_waitcnt lgkmcnt(0)
	s_barrier
	s_waitcnt lgkmcnt(0)
	v_mfma_f32_16x16x32_bf16 v[60:63], v[146:149], v[178:181], v[60:63]
	v_mfma_f32_16x16x32_bf16 v[56:59], v[154:157], v[178:181], v[56:59]
	v_mfma_f32_16x16x32_bf16 v[52:55], v[146:149], v[186:189], v[52:55]
	v_mfma_f32_16x16x32_bf16 v[44:47], v[154:157], v[186:189], v[44:47]
	v_mfma_f32_16x16x32_bf16 v[36:39], v[146:149], v[194:197], v[36:39]
	v_mfma_f32_16x16x32_bf16 v[28:31], v[154:157], v[194:197], v[28:31]
	v_mfma_f32_16x16x32_bf16 v[20:23], v[146:149], v[202:205], v[20:23]
	v_mfma_f32_16x16x32_bf16 v[12:15], v[154:157], v[202:205], v[12:15]
	v_mfma_f32_16x16x32_bf16 v[60:63], v[150:153], v[182:185], v[60:63]
	v_mfma_f32_16x16x32_bf16 v[56:59], v[158:161], v[182:185], v[56:59]
	v_mfma_f32_16x16x32_bf16 v[52:55], v[150:153], v[190:193], v[52:55]
	v_mfma_f32_16x16x32_bf16 v[44:47], v[158:161], v[190:193], v[44:47]
	v_mfma_f32_16x16x32_bf16 v[36:39], v[150:153], v[198:201], v[36:39]
	v_mfma_f32_16x16x32_bf16 v[28:31], v[158:161], v[198:201], v[28:31]
	v_mfma_f32_16x16x32_bf16 v[20:23], v[150:153], v[206:209], v[20:23]
	v_mfma_f32_16x16x32_bf16 v[12:15], v[158:161], v[206:209], v[12:15]
	v_mfma_f32_16x16x32_bf16 v[48:51], v[162:165], v[178:181], v[48:51]
	v_mfma_f32_16x16x32_bf16 v[40:43], v[170:173], v[178:181], v[40:43]
	v_mfma_f32_16x16x32_bf16 v[32:35], v[162:165], v[186:189], v[32:35]
	v_mfma_f32_16x16x32_bf16 v[24:27], v[170:173], v[186:189], v[24:27]
	v_mfma_f32_16x16x32_bf16 v[16:19], v[162:165], v[194:197], v[16:19]
	v_mfma_f32_16x16x32_bf16 v[8:11], v[170:173], v[194:197], v[8:11]
	v_mfma_f32_16x16x32_bf16 v[4:7], v[162:165], v[202:205], v[4:7]
	v_mfma_f32_16x16x32_bf16 v[0:3], v[170:173], v[202:205], v[0:3]
	v_mfma_f32_16x16x32_bf16 v[48:51], v[166:169], v[182:185], v[48:51]
	v_mfma_f32_16x16x32_bf16 v[40:43], v[174:177], v[182:185], v[40:43]
	v_mfma_f32_16x16x32_bf16 v[32:35], v[166:169], v[190:193], v[32:35]
	v_mfma_f32_16x16x32_bf16 v[24:27], v[174:177], v[190:193], v[24:27]
	v_mfma_f32_16x16x32_bf16 v[16:19], v[166:169], v[198:201], v[16:19]
	v_mfma_f32_16x16x32_bf16 v[8:11], v[174:177], v[198:201], v[8:11]
	v_mfma_f32_16x16x32_bf16 v[4:7], v[166:169], v[206:209], v[4:7]
	v_mfma_f32_16x16x32_bf16 v[0:3], v[174:177], v[206:209], v[0:3]
	s_barrier
	v_add_u32_e32 v158, vcc_lo, v141
	v_add_u32_e32 v174, vcc_hi, v141
	ds_read_b128 v[146:149], v158
	ds_read_b128 v[150:153], v158 offset:1024
	ds_read_b128 v[154:157], v158 offset:2048
	ds_read_b128 v[158:161], v158 offset:3072
	ds_read_b128 v[162:165], v174
	ds_read_b128 v[166:169], v174 offset:1024
	ds_read_b128 v[170:173], v174 offset:2048
	ds_read_b128 v[174:177], v174 offset:3072
	s_mov_b32 m0, s72
	v_lshl_add_u64 v[218:219], s[38:39], 0, v[128:129]
	ds_read_b128 v[178:181], v145 offset:32768
	ds_read_b128 v[182:185], v145 offset:33792
	ds_read_b128 v[186:189], v145 offset:34816
	ds_read_b128 v[190:193], v145 offset:35840
	ds_read_b128 v[194:197], v145 offset:36864
	ds_read_b128 v[198:201], v145 offset:37888
	ds_read_b128 v[202:205], v145 offset:38912
	ds_read_b128 v[206:209], v145 offset:39936
	global_load_lds_dwordx4 v[218:219], off
	v_lshl_add_u64 v[218:219], s[38:39], 0, v[132:133]
	s_mov_b32 m0, s73
	s_nop 0
	global_load_lds_dwordx4 v[218:219], off
	s_waitcnt vmcnt(8)
	s_waitcnt lgkmcnt(0)
	s_barrier
	s_waitcnt lgkmcnt(0)
	v_mfma_f32_16x16x32_bf16 v[124:127], v[146:149], v[178:181], v[124:127]
	v_mfma_f32_16x16x32_bf16 v[120:123], v[154:157], v[178:181], v[120:123]
	v_mfma_f32_16x16x32_bf16 v[116:119], v[146:149], v[186:189], v[116:119]
	v_mfma_f32_16x16x32_bf16 v[108:111], v[154:157], v[186:189], v[108:111]
	v_mfma_f32_16x16x32_bf16 v[100:103], v[146:149], v[194:197], v[100:103]
	v_mfma_f32_16x16x32_bf16 v[92:95], v[154:157], v[194:197], v[92:95]
	v_mfma_f32_16x16x32_bf16 v[84:87], v[146:149], v[202:205], v[84:87]
	v_mfma_f32_16x16x32_bf16 v[76:79], v[154:157], v[202:205], v[76:79]
	v_mfma_f32_16x16x32_bf16 v[124:127], v[150:153], v[182:185], v[124:127]
	v_mfma_f32_16x16x32_bf16 v[120:123], v[158:161], v[182:185], v[120:123]
	v_mfma_f32_16x16x32_bf16 v[116:119], v[150:153], v[190:193], v[116:119]
	v_mfma_f32_16x16x32_bf16 v[108:111], v[158:161], v[190:193], v[108:111]
	v_mfma_f32_16x16x32_bf16 v[100:103], v[150:153], v[198:201], v[100:103]
	v_mfma_f32_16x16x32_bf16 v[92:95], v[158:161], v[198:201], v[92:95]
	v_mfma_f32_16x16x32_bf16 v[84:87], v[150:153], v[206:209], v[84:87]
	v_mfma_f32_16x16x32_bf16 v[76:79], v[158:161], v[206:209], v[76:79]
	v_mfma_f32_16x16x32_bf16 v[112:115], v[162:165], v[178:181], v[112:115]
	v_mfma_f32_16x16x32_bf16 v[104:107], v[170:173], v[178:181], v[104:107]
	v_mfma_f32_16x16x32_bf16 v[96:99], v[162:165], v[186:189], v[96:99]
	v_mfma_f32_16x16x32_bf16 v[88:91], v[170:173], v[186:189], v[88:91]
	v_mfma_f32_16x16x32_bf16 v[80:83], v[162:165], v[194:197], v[80:83]
	v_mfma_f32_16x16x32_bf16 v[72:75], v[170:173], v[194:197], v[72:75]
	v_mfma_f32_16x16x32_bf16 v[68:71], v[162:165], v[202:205], v[68:71]
	v_mfma_f32_16x16x32_bf16 v[64:67], v[170:173], v[202:205], v[64:67]
	v_mfma_f32_16x16x32_bf16 v[112:115], v[166:169], v[182:185], v[112:115]
	v_mfma_f32_16x16x32_bf16 v[104:107], v[174:177], v[182:185], v[104:107]
	v_mfma_f32_16x16x32_bf16 v[96:99], v[166:169], v[190:193], v[96:99]
	v_mfma_f32_16x16x32_bf16 v[88:91], v[174:177], v[190:193], v[88:91]
	v_mfma_f32_16x16x32_bf16 v[80:83], v[166:169], v[198:201], v[80:83]
	v_mfma_f32_16x16x32_bf16 v[72:75], v[174:177], v[198:201], v[72:75]
	v_mfma_f32_16x16x32_bf16 v[68:71], v[166:169], v[206:209], v[68:71]
	v_mfma_f32_16x16x32_bf16 v[64:67], v[174:177], v[206:209], v[64:67]
	s_barrier
	s_mov_b32 m0, s96
	v_lshl_add_u64 v[210:211], v[210:211], 0, s[14:15]
	ds_read_b128 v[178:181], v145 offset:49152
	ds_read_b128 v[182:185], v145 offset:50176
	ds_read_b128 v[186:189], v145 offset:51200
	ds_read_b128 v[190:193], v145 offset:52224
	ds_read_b128 v[194:197], v145 offset:53248
	ds_read_b128 v[198:201], v145 offset:54272
	ds_read_b128 v[202:205], v145 offset:55296
	ds_read_b128 v[206:209], v145 offset:56320
	global_load_lds_dwordx4 v[210:211], off
	v_lshl_add_u64 v[210:211], v[212:213], 0, s[14:15]
	s_mov_b32 m0, s95
	s_nop 0
	global_load_lds_dwordx4 v[210:211], off
	v_lshl_add_u64 v[210:211], s[36:37], 0, v[130:131]
	s_mov_b32 m0, s97
	s_nop 0
	global_load_lds_dwordx4 v[210:211], off
	v_lshl_add_u64 v[210:211], s[36:37], 0, v[134:135]
	s_mov_b32 m0, s83
	s_nop 0
	global_load_lds_dwordx4 v[210:211], off
	v_lshl_add_u64 v[210:211], v[214:215], 0, s[14:15]
	s_mov_b32 m0, s75
	s_nop 0
	global_load_lds_dwordx4 v[210:211], off
	v_lshl_add_u64 v[210:211], v[216:217], 0, s[14:15]
	s_mov_b32 m0, s76
	s_nop 0
	global_load_lds_dwordx4 v[210:211], off
	s_waitcnt vmcnt(8)
	s_waitcnt lgkmcnt(0)
	s_barrier
	s_waitcnt lgkmcnt(0)
	v_mfma_f32_16x16x32_bf16 v[60:63], v[146:149], v[178:181], v[60:63]
	v_mfma_f32_16x16x32_bf16 v[56:59], v[154:157], v[178:181], v[56:59]
	v_mfma_f32_16x16x32_bf16 v[52:55], v[146:149], v[186:189], v[52:55]
	v_mfma_f32_16x16x32_bf16 v[44:47], v[154:157], v[186:189], v[44:47]
	v_mfma_f32_16x16x32_bf16 v[36:39], v[146:149], v[194:197], v[36:39]
	v_mfma_f32_16x16x32_bf16 v[28:31], v[154:157], v[194:197], v[28:31]
	v_mfma_f32_16x16x32_bf16 v[20:23], v[146:149], v[202:205], v[20:23]
	v_mfma_f32_16x16x32_bf16 v[12:15], v[154:157], v[202:205], v[12:15]
	v_mfma_f32_16x16x32_bf16 v[60:63], v[150:153], v[182:185], v[60:63]
	v_mfma_f32_16x16x32_bf16 v[56:59], v[158:161], v[182:185], v[56:59]
	v_mfma_f32_16x16x32_bf16 v[52:55], v[150:153], v[190:193], v[52:55]
	v_mfma_f32_16x16x32_bf16 v[44:47], v[158:161], v[190:193], v[44:47]
	v_mfma_f32_16x16x32_bf16 v[36:39], v[150:153], v[198:201], v[36:39]
	v_mfma_f32_16x16x32_bf16 v[28:31], v[158:161], v[198:201], v[28:31]
	v_mfma_f32_16x16x32_bf16 v[20:23], v[150:153], v[206:209], v[20:23]
	v_mfma_f32_16x16x32_bf16 v[12:15], v[158:161], v[206:209], v[12:15]
	v_mfma_f32_16x16x32_bf16 v[48:51], v[162:165], v[178:181], v[48:51]
	v_mfma_f32_16x16x32_bf16 v[40:43], v[170:173], v[178:181], v[40:43]
	v_mfma_f32_16x16x32_bf16 v[32:35], v[162:165], v[186:189], v[32:35]
	v_mfma_f32_16x16x32_bf16 v[24:27], v[170:173], v[186:189], v[24:27]
	v_mfma_f32_16x16x32_bf16 v[16:19], v[162:165], v[194:197], v[16:19]
	v_mfma_f32_16x16x32_bf16 v[8:11], v[170:173], v[194:197], v[8:11]
	v_mfma_f32_16x16x32_bf16 v[4:7], v[162:165], v[202:205], v[4:7]
	v_mfma_f32_16x16x32_bf16 v[0:3], v[170:173], v[202:205], v[0:3]
	v_mfma_f32_16x16x32_bf16 v[48:51], v[166:169], v[182:185], v[48:51]
	v_mfma_f32_16x16x32_bf16 v[40:43], v[174:177], v[182:185], v[40:43]
	v_mfma_f32_16x16x32_bf16 v[32:35], v[166:169], v[190:193], v[32:35]
	v_mfma_f32_16x16x32_bf16 v[24:27], v[174:177], v[190:193], v[24:27]
	v_mfma_f32_16x16x32_bf16 v[16:19], v[166:169], v[198:201], v[16:19]
	v_mfma_f32_16x16x32_bf16 v[8:11], v[174:177], v[198:201], v[8:11]
	v_mfma_f32_16x16x32_bf16 v[4:7], v[166:169], v[206:209], v[4:7]
	v_mfma_f32_16x16x32_bf16 v[0:3], v[174:177], v[206:209], v[0:3]
	s_barrier
	s_movk_i32 s38, 0x100
	s_andn2_b64 vcc, exec, s[34:35]
	s_mov_b64 s[36:37], -1
	s_mov_b64 s[34:35], 0
	s_cbranch_vccz .LBB0_997
	s_and_b64 vcc, exec, s[16:17]
	s_cbranch_vccz .LBB0_1000
	s_barrier

.LBB0_1067:
	ds_read_b128 v[16:19], v188
	ds_read_b128 v[20:23], v188 offset:1024
	ds_read_b128 v[24:27], v188 offset:2048
	ds_read_b128 v[28:31], v188 offset:3072
	ds_read_b128 v[0:3], v189
	ds_read_b128 v[4:7], v189 offset:1024
	ds_read_b128 v[8:11], v189 offset:2048
	ds_read_b128 v[12:15], v189 offset:3072
	s_add_u32 s30, s28, 0xfffc0080
	s_addc_u32 s31, s29, -1
	s_cmp_eq_u32 s74, 12
	s_cselect_b32 s35, s23, s31
	s_cselect_b32 s34, s70, s30
	s_cselect_b32 s31, s21, s73
	s_cselect_b32 s30, s71, s72
	v_lshl_add_u64 v[218:219], s[28:29], 0, v[168:169]
	s_add_i32 m0, s40, 0xc000
	ds_read_b128 v[176:179], v190
	ds_read_b128 v[180:183], v190 offset:1024
	ds_read_b128 v[194:197], v190 offset:2048
	ds_read_b128 v[198:201], v190 offset:3072
	ds_read_b128 v[202:205], v190 offset:4096
	ds_read_b128 v[206:209], v190 offset:5120
	ds_read_b128 v[210:213], v190 offset:6144
	ds_read_b128 v[214:217], v190 offset:7168
	global_load_lds_dwordx4 v[218:219], off
	v_lshl_add_u64 v[218:219], s[28:29], 0, v[170:171]
	s_add_i32 m0, s40, 0xe000
	s_nop 0
	global_load_lds_dwordx4 v[218:219], off
	s_waitcnt vmcnt(8)
	s_waitcnt lgkmcnt(0)
	s_barrier
	s_waitcnt lgkmcnt(0)
	v_mfma_scale_f32_16x16x128_f8f6f4 v[156:159], v[16:23], v[176:183], v[156:159], v184, v184 op_sel_hi:[0,0,0]
	v_mfma_scale_f32_16x16x128_f8f6f4 v[152:155], v[24:31], v[176:183], v[152:155], v184, v184 op_sel_hi:[0,0,0]
	v_mfma_scale_f32_16x16x128_f8f6f4 v[140:143], v[16:23], v[194:201], v[140:143], v184, v184 op_sel_hi:[0,0,0]
	v_mfma_scale_f32_16x16x128_f8f6f4 v[136:139], v[24:31], v[194:201], v[136:139], v184, v184 op_sel_hi:[0,0,0]
	v_mfma_scale_f32_16x16x128_f8f6f4 v[124:127], v[16:23], v[202:209], v[124:127], v184, v184 op_sel_hi:[0,0,0]
	v_mfma_scale_f32_16x16x128_f8f6f4 v[120:123], v[24:31], v[202:209], v[120:123], v184, v184 op_sel_hi:[0,0,0]
	v_mfma_scale_f32_16x16x128_f8f6f4 v[108:111], v[16:23], v[210:217], v[108:111], v184, v184 op_sel_hi:[0,0,0]
	v_mfma_scale_f32_16x16x128_f8f6f4 v[104:107], v[24:31], v[210:217], v[104:107], v184, v184 op_sel_hi:[0,0,0]
	v_mfma_scale_f32_16x16x128_f8f6f4 v[148:151], v[0:7], v[176:183], v[148:151], v184, v184 op_sel_hi:[0,0,0]
	v_mfma_scale_f32_16x16x128_f8f6f4 v[144:147], v[8:15], v[176:183], v[144:147], v184, v184 op_sel_hi:[0,0,0]
	v_mfma_scale_f32_16x16x128_f8f6f4 v[132:135], v[0:7], v[194:201], v[132:135], v184, v184 op_sel_hi:[0,0,0]
	v_mfma_scale_f32_16x16x128_f8f6f4 v[128:131], v[8:15], v[194:201], v[128:131], v184, v184 op_sel_hi:[0,0,0]
	v_mfma_scale_f32_16x16x128_f8f6f4 v[116:119], v[0:7], v[202:209], v[116:119], v184, v184 op_sel_hi:[0,0,0]
	v_mfma_scale_f32_16x16x128_f8f6f4 v[112:115], v[8:15], v[202:209], v[112:115], v184, v184 op_sel_hi:[0,0,0]
	v_mfma_scale_f32_16x16x128_f8f6f4 v[100:103], v[0:7], v[210:217], v[100:103], v184, v184 op_sel_hi:[0,0,0]
	v_mfma_scale_f32_16x16x128_f8f6f4 v[96:99], v[8:15], v[210:217], v[96:99], v184, v184 op_sel_hi:[0,0,0]
	s_barrier
	s_add_i32 s75, s65, s3
	v_lshl_add_u64 v[176:177], s[30:31], 0, v[164:165]
	s_mov_b32 m0, s75
	ds_read_b128 v[194:197], v190 offset:16384
	ds_read_b128 v[198:201], v190 offset:17408
	ds_read_b128 v[202:205], v190 offset:18432
	ds_read_b128 v[206:209], v190 offset:19456
	ds_read_b128 v[210:213], v190 offset:20480
	ds_read_b128 v[214:217], v190 offset:21504
	ds_read_b128 v[226:229], v190 offset:22528
	ds_read_b128 v[230:233], v190 offset:23552
	global_load_lds_dwordx4 v[176:177], off
	s_add_i32 m0, s75, 0x2000
	s_add_u32 s76, s30, 0x40000
	v_lshl_add_u64 v[178:179], s[30:31], 0, v[160:161]
	s_addc_u32 s77, s31, 0
	s_add_i32 s75, s66, s3
	global_load_lds_dwordx4 v[178:179], off
	v_lshl_add_u64 v[180:181], s[76:77], 0, v[164:165]
	s_mov_b32 m0, s75
	v_lshl_add_u64 v[182:183], s[34:35], 0, v[162:163]
	global_load_lds_dwordx4 v[180:181], off
	v_lshl_add_u64 v[180:181], s[76:77], 0, v[160:161]
	s_add_i32 m0, s75, 0x2000
	s_nop 0
	global_load_lds_dwordx4 v[180:181], off
	v_lshl_add_u64 v[180:181], s[34:35], 0, v[166:167]
	s_mov_b32 m0, s40
	s_nop 0
	global_load_lds_dwordx4 v[180:181], off
	s_mov_b32 m0, s41
	s_nop 0
	global_load_lds_dwordx4 v[182:183], off
	s_waitcnt vmcnt(8)
	s_waitcnt lgkmcnt(0)
	s_barrier
	s_waitcnt lgkmcnt(0)
	v_mfma_scale_f32_16x16x128_f8f6f4 v[92:95], v[16:23], v[194:201], v[92:95], v184, v184 op_sel_hi:[0,0,0]
	v_mfma_scale_f32_16x16x128_f8f6f4 v[88:91], v[24:31], v[194:201], v[88:91], v184, v184 op_sel_hi:[0,0,0]
	v_mfma_scale_f32_16x16x128_f8f6f4 v[76:79], v[16:23], v[202:209], v[76:79], v184, v184 op_sel_hi:[0,0,0]
	v_mfma_scale_f32_16x16x128_f8f6f4 v[72:75], v[24:31], v[202:209], v[72:75], v184, v184 op_sel_hi:[0,0,0]
	v_mfma_scale_f32_16x16x128_f8f6f4 v[60:63], v[16:23], v[210:217], v[60:63], v184, v184 op_sel_hi:[0,0,0]
	v_mfma_scale_f32_16x16x128_f8f6f4 v[56:59], v[24:31], v[210:217], v[56:59], v184, v184 op_sel_hi:[0,0,0]
	v_mfma_scale_f32_16x16x128_f8f6f4 v[44:47], v[16:23], v[226:233], v[44:47], v184, v184 op_sel_hi:[0,0,0]
	v_mfma_scale_f32_16x16x128_f8f6f4 v[40:43], v[24:31], v[226:233], v[40:43], v184, v184 op_sel_hi:[0,0,0]
	v_mfma_scale_f32_16x16x128_f8f6f4 v[84:87], v[0:7], v[194:201], v[84:87], v184, v184 op_sel_hi:[0,0,0]
	v_mfma_scale_f32_16x16x128_f8f6f4 v[80:83], v[8:15], v[194:201], v[80:83], v184, v184 op_sel_hi:[0,0,0]
	v_mfma_scale_f32_16x16x128_f8f6f4 v[68:71], v[0:7], v[202:209], v[68:71], v184, v184 op_sel_hi:[0,0,0]
	v_mfma_scale_f32_16x16x128_f8f6f4 v[64:67], v[8:15], v[202:209], v[64:67], v184, v184 op_sel_hi:[0,0,0]
	v_mfma_scale_f32_16x16x128_f8f6f4 v[52:55], v[0:7], v[210:217], v[52:55], v184, v184 op_sel_hi:[0,0,0]
	v_mfma_scale_f32_16x16x128_f8f6f4 v[48:51], v[8:15], v[210:217], v[48:51], v184, v184 op_sel_hi:[0,0,0]
	v_mfma_scale_f32_16x16x128_f8f6f4 v[36:39], v[0:7], v[226:233], v[36:39], v184, v184 op_sel_hi:[0,0,0]
	v_mfma_scale_f32_16x16x128_f8f6f4 v[32:35], v[8:15], v[226:233], v[32:35], v184, v184 op_sel_hi:[0,0,0]
	s_barrier
	s_add_i32 s75, 0, 0x18000
	s_add_i32 s76, 0, 0x1c000
	v_add_u32_e32 v12, s75, v186
	v_add_u32_e32 v28, s76, v186
	ds_read_b128 v[0:3], v12
	ds_read_b128 v[4:7], v12 offset:1024
	ds_read_b128 v[8:11], v12 offset:2048
	ds_read_b128 v[12:15], v12 offset:3072
	ds_read_b128 v[16:19], v28
	ds_read_b128 v[20:23], v28 offset:1024
	ds_read_b128 v[24:27], v28 offset:2048
	ds_read_b128 v[28:31], v28 offset:3072
	s_add_u32 s34, s34, 0x40000
	s_addc_u32 s35, s35, 0
	s_mov_b32 m0, s44
	v_lshl_add_u64 v[218:219], s[34:35], 0, v[166:167]
	ds_read_b128 v[194:197], v190 offset:32768
	ds_read_b128 v[198:201], v190 offset:33792
	ds_read_b128 v[202:205], v190 offset:34816
	ds_read_b128 v[206:209], v190 offset:35840
	ds_read_b128 v[210:213], v190 offset:36864
	ds_read_b128 v[214:217], v190 offset:37888
	ds_read_b128 v[226:229], v190 offset:38912
	ds_read_b128 v[230:233], v190 offset:39936
	global_load_lds_dwordx4 v[218:219], off
	v_lshl_add_u64 v[218:219], s[34:35], 0, v[162:163]
	s_mov_b32 m0, s45
	s_nop 0
	global_load_lds_dwordx4 v[218:219], off
	s_waitcnt vmcnt(8)
	s_waitcnt lgkmcnt(0)
	s_barrier
	s_waitcnt lgkmcnt(0)
	v_mfma_scale_f32_16x16x128_f8f6f4 v[156:159], v[0:7], v[194:201], v[156:159], v184, v184 op_sel_hi:[0,0,0]
	v_mfma_scale_f32_16x16x128_f8f6f4 v[152:155], v[8:15], v[194:201], v[152:155], v184, v184 op_sel_hi:[0,0,0]
	v_mfma_scale_f32_16x16x128_f8f6f4 v[140:143], v[0:7], v[202:209], v[140:143], v184, v184 op_sel_hi:[0,0,0]
	v_mfma_scale_f32_16x16x128_f8f6f4 v[136:139], v[8:15], v[202:209], v[136:139], v184, v184 op_sel_hi:[0,0,0]
	v_mfma_scale_f32_16x16x128_f8f6f4 v[124:127], v[0:7], v[210:217], v[124:127], v184, v184 op_sel_hi:[0,0,0]
	v_mfma_scale_f32_16x16x128_f8f6f4 v[120:123], v[8:15], v[210:217], v[120:123], v184, v184 op_sel_hi:[0,0,0]
	v_mfma_scale_f32_16x16x128_f8f6f4 v[108:111], v[0:7], v[226:233], v[108:111], v184, v184 op_sel_hi:[0,0,0]
	v_mfma_scale_f32_16x16x128_f8f6f4 v[104:107], v[8:15], v[226:233], v[104:107], v184, v184 op_sel_hi:[0,0,0]
	v_mfma_scale_f32_16x16x128_f8f6f4 v[148:151], v[16:23], v[194:201], v[148:151], v184, v184 op_sel_hi:[0,0,0]
	v_mfma_scale_f32_16x16x128_f8f6f4 v[144:147], v[24:31], v[194:201], v[144:147], v184, v184 op_sel_hi:[0,0,0]
	v_mfma_scale_f32_16x16x128_f8f6f4 v[132:135], v[16:23], v[202:209], v[132:135], v184, v184 op_sel_hi:[0,0,0]
	v_mfma_scale_f32_16x16x128_f8f6f4 v[128:131], v[24:31], v[202:209], v[128:131], v184, v184 op_sel_hi:[0,0,0]
	v_mfma_scale_f32_16x16x128_f8f6f4 v[116:119], v[16:23], v[210:217], v[116:119], v184, v184 op_sel_hi:[0,0,0]
	v_mfma_scale_f32_16x16x128_f8f6f4 v[112:115], v[24:31], v[210:217], v[112:115], v184, v184 op_sel_hi:[0,0,0]
	v_mfma_scale_f32_16x16x128_f8f6f4 v[100:103], v[16:23], v[226:233], v[100:103], v184, v184 op_sel_hi:[0,0,0]
	v_mfma_scale_f32_16x16x128_f8f6f4 v[96:99], v[24:31], v[226:233], v[96:99], v184, v184 op_sel_hi:[0,0,0]
	s_barrier
	s_add_i32 s34, s75, s3
	v_lshl_add_u64 v[176:177], v[176:177], 0, s[16:17]
	s_mov_b32 m0, s34
	ds_read_b128 v[194:197], v190 offset:49152
	ds_read_b128 v[198:201], v190 offset:50176
	ds_read_b128 v[202:205], v190 offset:51200
	ds_read_b128 v[206:209], v190 offset:52224
	ds_read_b128 v[210:213], v190 offset:53248
	ds_read_b128 v[214:217], v190 offset:54272
	ds_read_b128 v[226:229], v190 offset:55296
	ds_read_b128 v[230:233], v190 offset:56320
	global_load_lds_dwordx4 v[176:177], off
	s_add_i32 m0, s34, 0x2000
	s_add_u32 s30, s30, 0x40080
	v_lshl_add_u64 v[176:177], v[178:179], 0, s[16:17]
	s_addc_u32 s31, s31, 0
	s_add_i32 s34, s76, s3
	global_load_lds_dwordx4 v[176:177], off
	v_lshl_add_u64 v[176:177], s[30:31], 0, v[164:165]
	s_mov_b32 m0, s34
	s_nop 0
	global_load_lds_dwordx4 v[176:177], off
	v_lshl_add_u64 v[176:177], s[30:31], 0, v[160:161]
	s_add_i32 m0, s34, 0x2000
	s_nop 0
	global_load_lds_dwordx4 v[176:177], off
	v_lshl_add_u64 v[176:177], v[180:181], 0, s[16:17]
	s_mov_b32 m0, s61
	s_nop 0
	global_load_lds_dwordx4 v[176:177], off
	v_lshl_add_u64 v[176:177], v[182:183], 0, s[16:17]
	s_mov_b32 m0, s62
	s_nop 0
	global_load_lds_dwordx4 v[176:177], off
	s_waitcnt vmcnt(8)
	s_waitcnt lgkmcnt(0)
	s_barrier
	s_waitcnt lgkmcnt(0)
	v_mfma_scale_f32_16x16x128_f8f6f4 v[92:95], v[0:7], v[194:201], v[92:95], v184, v184 op_sel_hi:[0,0,0]
	v_mfma_scale_f32_16x16x128_f8f6f4 v[88:91], v[8:15], v[194:201], v[88:91], v184, v184 op_sel_hi:[0,0,0]
	v_mfma_scale_f32_16x16x128_f8f6f4 v[76:79], v[0:7], v[202:209], v[76:79], v184, v184 op_sel_hi:[0,0,0]
	v_mfma_scale_f32_16x16x128_f8f6f4 v[72:75], v[8:15], v[202:209], v[72:75], v184, v184 op_sel_hi:[0,0,0]
	v_mfma_scale_f32_16x16x128_f8f6f4 v[60:63], v[0:7], v[210:217], v[60:63], v184, v184 op_sel_hi:[0,0,0]
	v_mfma_scale_f32_16x16x128_f8f6f4 v[56:59], v[8:15], v[210:217], v[56:59], v184, v184 op_sel_hi:[0,0,0]
	v_mfma_scale_f32_16x16x128_f8f6f4 v[44:47], v[0:7], v[226:233], v[44:47], v184, v184 op_sel_hi:[0,0,0]
	v_mfma_scale_f32_16x16x128_f8f6f4 v[40:43], v[8:15], v[226:233], v[40:43], v184, v184 op_sel_hi:[0,0,0]
	v_mfma_scale_f32_16x16x128_f8f6f4 v[84:87], v[16:23], v[194:201], v[84:87], v184, v184 op_sel_hi:[0,0,0]
	v_mfma_scale_f32_16x16x128_f8f6f4 v[80:83], v[24:31], v[194:201], v[80:83], v184, v184 op_sel_hi:[0,0,0]
	v_mfma_scale_f32_16x16x128_f8f6f4 v[68:71], v[16:23], v[202:209], v[68:71], v184, v184 op_sel_hi:[0,0,0]
	v_mfma_scale_f32_16x16x128_f8f6f4 v[64:67], v[24:31], v[202:209], v[64:67], v184, v184 op_sel_hi:[0,0,0]
	v_mfma_scale_f32_16x16x128_f8f6f4 v[52:55], v[16:23], v[210:217], v[52:55], v184, v184 op_sel_hi:[0,0,0]
	v_mfma_scale_f32_16x16x128_f8f6f4 v[48:51], v[24:31], v[210:217], v[48:51], v184, v184 op_sel_hi:[0,0,0]
	v_mfma_scale_f32_16x16x128_f8f6f4 v[36:39], v[16:23], v[226:233], v[36:39], v184, v184 op_sel_hi:[0,0,0]
	v_mfma_scale_f32_16x16x128_f8f6f4 v[32:35], v[24:31], v[226:233], v[32:35], v184, v184 op_sel_hi:[0,0,0]
	s_barrier
	s_add_i32 s74, s74, 2
	s_add_u32 s28, s28, 0x100
	s_addc_u32 s29, s29, 0
	s_add_u32 s72, s72, 0x100
	s_addc_u32 s73, s73, 0
	s_cmp_gt_u32 s74, 13
	s_cbranch_scc0 .LBB0_1067
	s_and_b64 vcc, exec, s[18:19]
	s_cbranch_vccz .LBB0_1070
	s_barrier

.LBB0_1257:
	v_add_u32_e32 v0, 0, v192
	v_add_u32_e32 v1, 0x10000, v0
	v_add_u32_e32 v12, 0x14000, v0
	ds_read_b128 v[16:19], v1
	ds_read_b128 v[20:23], v1 offset:1024
	ds_read_b128 v[24:27], v1 offset:2048
	ds_read_b128 v[28:31], v1 offset:3072
	ds_read_b128 v[0:3], v12
	ds_read_b128 v[4:7], v12 offset:1024
	ds_read_b128 v[8:11], v12 offset:2048
	ds_read_b128 v[12:15], v12 offset:3072
	s_cmp_lg_u32 s77, 40
	s_cselect_b64 s[34:35], -1, 0
	s_add_u32 s30, s20, s28
	s_addc_u32 s31, s21, s29
	s_add_u32 s30, s30, s26
	s_addc_u32 s31, s31, s27
	v_lshl_add_u64 v[184:185], s[30:31], 0, v[160:161]
	v_lshl_add_u64 v[184:185], v[184:185], 0, s[16:17]
	s_add_i32 m0, s40, 0xc000
	v_mov_b32_e32 v173, v161
	ds_read_b128 v[176:179], v193
	ds_read_b128 v[180:183], v193 offset:1024
	ds_read_b128 v[194:197], v193 offset:2048
	ds_read_b128 v[198:201], v193 offset:3072
	ds_read_b128 v[202:205], v193 offset:4096
	ds_read_b128 v[206:209], v193 offset:5120
	ds_read_b128 v[210:213], v193 offset:6144
	ds_read_b128 v[214:217], v193 offset:7168
	global_load_lds_dwordx4 v[184:185], off
	v_lshl_add_u64 v[184:185], s[30:31], 0, v[172:173]
	v_lshl_add_u64 v[184:185], v[184:185], 0, s[16:17]
	s_add_i32 m0, s40, 0xe000
	s_nop 0
	global_load_lds_dwordx4 v[184:185], off
	s_waitcnt vmcnt(8)
	s_waitcnt lgkmcnt(0)
	s_barrier
	s_waitcnt lgkmcnt(0)
	v_mfma_scale_f32_16x16x128_f8f6f4 v[156:159], v[16:23], v[176:183], v[156:159], v190, v190 op_sel_hi:[0,0,0]
	v_mfma_scale_f32_16x16x128_f8f6f4 v[152:155], v[24:31], v[176:183], v[152:155], v190, v190 op_sel_hi:[0,0,0]
	v_mfma_scale_f32_16x16x128_f8f6f4 v[140:143], v[16:23], v[194:201], v[140:143], v190, v190 op_sel_hi:[0,0,0]
	v_mfma_scale_f32_16x16x128_f8f6f4 v[136:139], v[24:31], v[194:201], v[136:139], v190, v190 op_sel_hi:[0,0,0]
	v_mfma_scale_f32_16x16x128_f8f6f4 v[124:127], v[16:23], v[202:209], v[124:127], v190, v190 op_sel_hi:[0,0,0]
	v_mfma_scale_f32_16x16x128_f8f6f4 v[120:123], v[24:31], v[202:209], v[120:123], v190, v190 op_sel_hi:[0,0,0]
	v_mfma_scale_f32_16x16x128_f8f6f4 v[108:111], v[16:23], v[210:217], v[108:111], v190, v190 op_sel_hi:[0,0,0]
	v_mfma_scale_f32_16x16x128_f8f6f4 v[104:107], v[24:31], v[210:217], v[104:107], v190, v190 op_sel_hi:[0,0,0]
	v_mfma_scale_f32_16x16x128_f8f6f4 v[148:151], v[0:7], v[176:183], v[148:151], v190, v190 op_sel_hi:[0,0,0]
	v_mfma_scale_f32_16x16x128_f8f6f4 v[144:147], v[8:15], v[176:183], v[144:147], v190, v190 op_sel_hi:[0,0,0]
	v_mfma_scale_f32_16x16x128_f8f6f4 v[132:135], v[0:7], v[194:201], v[132:135], v190, v190 op_sel_hi:[0,0,0]
	v_mfma_scale_f32_16x16x128_f8f6f4 v[128:131], v[8:15], v[194:201], v[128:131], v190, v190 op_sel_hi:[0,0,0]
	v_mfma_scale_f32_16x16x128_f8f6f4 v[116:119], v[0:7], v[202:209], v[116:119], v190, v190 op_sel_hi:[0,0,0]
	v_mfma_scale_f32_16x16x128_f8f6f4 v[112:115], v[8:15], v[202:209], v[112:115], v190, v190 op_sel_hi:[0,0,0]
	v_mfma_scale_f32_16x16x128_f8f6f4 v[100:103], v[0:7], v[210:217], v[100:103], v190, v190 op_sel_hi:[0,0,0]
	v_mfma_scale_f32_16x16x128_f8f6f4 v[96:99], v[8:15], v[210:217], v[96:99], v190, v190 op_sel_hi:[0,0,0]
	s_barrier
	s_or_b64 s[78:79], s[8:9], s[34:35]
	s_mov_b64 s[30:31], 0x80000
	s_andn2_b64 vcc, exec, s[78:79]
	v_mov_b64_e32 v[176:177], v[164:165]
	v_mov_b64_e32 v[178:179], v[162:163]
	v_mov_b64_e32 v[182:183], v[164:165]
	v_mov_b64_e32 v[184:185], v[162:163]
	v_mov_b32_e32 v194, v164
	v_mov_b32_e32 v195, v162
	v_mov_b32_e32 v196, v164
	v_mov_b32_e32 v197, v162
	s_cbranch_vccnz .LBB0_1259
	v_mov_b32_e32 v171, v161
	v_mov_b32_e32 v175, v161
	v_mov_b64_e32 v[176:177], v[174:175]
	v_mov_b64_e32 v[178:179], v[170:171]
	v_mov_b64_e32 v[182:183], v[172:173]
	v_mov_b64_e32 v[184:185], v[160:161]
	v_mov_b32_e32 v194, v172
	v_mov_b32_e32 v195, v160
	v_mov_b32_e32 v196, v174
	v_mov_b32_e32 v197, v170
	s_mov_b64 s[30:31], s[26:27]
.LBB0_1259:
	s_add_u32 s26, s20, s28
	s_addc_u32 s27, s21, s29
	s_add_u32 s78, s26, 0x100
	s_addc_u32 s79, s27, 0
	s_and_b64 s[26:27], s[34:35], exec
	s_cselect_b32 s27, s79, s75
	s_cselect_b32 s26, s78, s76
	s_add_u32 s78, s71, s28
	s_addc_u32 s79, s72, s29
	s_and_b64 s[34:35], s[34:35], exec
	s_cselect_b32 s35, s79, s73
	s_cselect_b32 s34, s78, s74
	s_mov_b32 m0, s41
	v_lshl_add_u64 v[172:173], s[34:35], 0, v[178:179]
	v_lshl_add_u64 v[170:171], s[34:35], 0, v[176:177]
	s_add_u32 s34, s34, s30
	ds_read_b128 v[198:201], v193 offset:16384
	ds_read_b128 v[202:205], v193 offset:17408
	ds_read_b128 v[206:209], v193 offset:18432
	ds_read_b128 v[210:213], v193 offset:19456
	ds_read_b128 v[214:217], v193 offset:20480
	ds_read_b128 v[218:221], v193 offset:21504
	ds_read_b128 v[226:229], v193 offset:22528
	ds_read_b128 v[230:233], v193 offset:23552
	global_load_lds_dwordx4 v[172:173], off
	s_mov_b32 m0, s44
	s_addc_u32 s35, s35, s31
	global_load_lds_dwordx4 v[170:171], off
	v_lshl_add_u64 v[180:181], s[34:35], 0, v[178:179]
	s_mov_b32 m0, s45
	v_lshl_add_u64 v[178:179], s[34:35], 0, v[176:177]
	global_load_lds_dwordx4 v[180:181], off
	s_mov_b32 m0, s60
	v_lshl_add_u64 v[174:175], s[26:27], 0, v[184:185]
	global_load_lds_dwordx4 v[178:179], off
	s_mov_b32 m0, s40
	v_lshl_add_u64 v[176:177], s[26:27], 0, v[182:183]
	global_load_lds_dwordx4 v[174:175], off
	s_mov_b32 m0, s61
	s_nop 0
	global_load_lds_dwordx4 v[176:177], off
	s_waitcnt vmcnt(8)
	s_waitcnt lgkmcnt(0)
	s_barrier
	s_waitcnt lgkmcnt(0)
	v_mfma_scale_f32_16x16x128_f8f6f4 v[92:95], v[16:23], v[198:205], v[92:95], v190, v190 op_sel_hi:[0,0,0]
	v_mfma_scale_f32_16x16x128_f8f6f4 v[88:91], v[24:31], v[198:205], v[88:91], v190, v190 op_sel_hi:[0,0,0]
	v_mfma_scale_f32_16x16x128_f8f6f4 v[76:79], v[16:23], v[206:213], v[76:79], v190, v190 op_sel_hi:[0,0,0]
	v_mfma_scale_f32_16x16x128_f8f6f4 v[72:75], v[24:31], v[206:213], v[72:75], v190, v190 op_sel_hi:[0,0,0]
	v_mfma_scale_f32_16x16x128_f8f6f4 v[60:63], v[16:23], v[214:221], v[60:63], v190, v190 op_sel_hi:[0,0,0]
	v_mfma_scale_f32_16x16x128_f8f6f4 v[56:59], v[24:31], v[214:221], v[56:59], v190, v190 op_sel_hi:[0,0,0]
	v_mfma_scale_f32_16x16x128_f8f6f4 v[44:47], v[16:23], v[226:233], v[44:47], v190, v190 op_sel_hi:[0,0,0]
	v_mfma_scale_f32_16x16x128_f8f6f4 v[40:43], v[24:31], v[226:233], v[40:43], v190, v190 op_sel_hi:[0,0,0]
	v_mfma_scale_f32_16x16x128_f8f6f4 v[84:87], v[0:7], v[198:205], v[84:87], v190, v190 op_sel_hi:[0,0,0]
	v_mfma_scale_f32_16x16x128_f8f6f4 v[80:83], v[8:15], v[198:205], v[80:83], v190, v190 op_sel_hi:[0,0,0]
	v_mfma_scale_f32_16x16x128_f8f6f4 v[68:71], v[0:7], v[206:213], v[68:71], v190, v190 op_sel_hi:[0,0,0]
	v_mfma_scale_f32_16x16x128_f8f6f4 v[64:67], v[8:15], v[206:213], v[64:67], v190, v190 op_sel_hi:[0,0,0]
	v_mfma_scale_f32_16x16x128_f8f6f4 v[52:55], v[0:7], v[214:221], v[52:55], v190, v190 op_sel_hi:[0,0,0]
	v_mfma_scale_f32_16x16x128_f8f6f4 v[48:51], v[8:15], v[214:221], v[48:51], v190, v190 op_sel_hi:[0,0,0]
	v_mfma_scale_f32_16x16x128_f8f6f4 v[36:39], v[0:7], v[226:233], v[36:39], v190, v190 op_sel_hi:[0,0,0]
	v_mfma_scale_f32_16x16x128_f8f6f4 v[32:35], v[8:15], v[226:233], v[32:35], v190, v190 op_sel_hi:[0,0,0]
	s_barrier
	s_add_i32 s34, 0, 0x18000
	s_add_i32 s35, 0, 0x1c000
	v_add_u32_e32 v12, s34, v192
	v_add_u32_e32 v28, s35, v192
	ds_read_b128 v[0:3], v12
	ds_read_b128 v[4:7], v12 offset:1024
	ds_read_b128 v[8:11], v12 offset:2048
	ds_read_b128 v[12:15], v12 offset:3072
	ds_read_b128 v[16:19], v28
	ds_read_b128 v[20:23], v28 offset:1024
	ds_read_b128 v[24:27], v28 offset:2048
	ds_read_b128 v[28:31], v28 offset:3072
	s_add_u32 s26, s26, s30
	s_addc_u32 s27, s27, s31
	s_mov_b32 m0, s62
	v_lshl_add_u64 v[184:185], s[26:27], 0, v[184:185]
	ds_read_b128 v[198:201], v193 offset:32768
	ds_read_b128 v[202:205], v193 offset:33792
	ds_read_b128 v[206:209], v193 offset:34816
	ds_read_b128 v[210:213], v193 offset:35840
	ds_read_b128 v[214:217], v193 offset:36864
	ds_read_b128 v[218:221], v193 offset:37888
	ds_read_b128 v[226:229], v193 offset:38912
	ds_read_b128 v[230:233], v193 offset:39936
	global_load_lds_dwordx4 v[184:185], off
	v_lshl_add_u64 v[182:183], s[26:27], 0, v[182:183]
	s_mov_b32 m0, s63
	s_nop 0
	global_load_lds_dwordx4 v[182:183], off
	s_waitcnt vmcnt(8)
	s_waitcnt lgkmcnt(0)
	s_barrier
	s_waitcnt lgkmcnt(0)
	v_mfma_scale_f32_16x16x128_f8f6f4 v[156:159], v[0:7], v[198:205], v[156:159], v190, v190 op_sel_hi:[0,0,0]
	v_mfma_scale_f32_16x16x128_f8f6f4 v[152:155], v[8:15], v[198:205], v[152:155], v190, v190 op_sel_hi:[0,0,0]
	v_mfma_scale_f32_16x16x128_f8f6f4 v[140:143], v[0:7], v[206:213], v[140:143], v190, v190 op_sel_hi:[0,0,0]
	v_mfma_scale_f32_16x16x128_f8f6f4 v[136:139], v[8:15], v[206:213], v[136:139], v190, v190 op_sel_hi:[0,0,0]
	v_mfma_scale_f32_16x16x128_f8f6f4 v[124:127], v[0:7], v[214:221], v[124:127], v190, v190 op_sel_hi:[0,0,0]
	v_mfma_scale_f32_16x16x128_f8f6f4 v[120:123], v[8:15], v[214:221], v[120:123], v190, v190 op_sel_hi:[0,0,0]
	v_mfma_scale_f32_16x16x128_f8f6f4 v[108:111], v[0:7], v[226:233], v[108:111], v190, v190 op_sel_hi:[0,0,0]
	v_mfma_scale_f32_16x16x128_f8f6f4 v[104:107], v[8:15], v[226:233], v[104:107], v190, v190 op_sel_hi:[0,0,0]
	v_mfma_scale_f32_16x16x128_f8f6f4 v[148:151], v[16:23], v[198:205], v[148:151], v190, v190 op_sel_hi:[0,0,0]
	v_mfma_scale_f32_16x16x128_f8f6f4 v[144:147], v[24:31], v[198:205], v[144:147], v190, v190 op_sel_hi:[0,0,0]
	v_mfma_scale_f32_16x16x128_f8f6f4 v[132:135], v[16:23], v[206:213], v[132:135], v190, v190 op_sel_hi:[0,0,0]
	v_mfma_scale_f32_16x16x128_f8f6f4 v[128:131], v[24:31], v[206:213], v[128:131], v190, v190 op_sel_hi:[0,0,0]
	v_mfma_scale_f32_16x16x128_f8f6f4 v[116:119], v[16:23], v[214:221], v[116:119], v190, v190 op_sel_hi:[0,0,0]
	v_mfma_scale_f32_16x16x128_f8f6f4 v[112:115], v[24:31], v[214:221], v[112:115], v190, v190 op_sel_hi:[0,0,0]
	v_mfma_scale_f32_16x16x128_f8f6f4 v[100:103], v[16:23], v[226:233], v[100:103], v190, v190 op_sel_hi:[0,0,0]
	v_mfma_scale_f32_16x16x128_f8f6f4 v[96:99], v[24:31], v[226:233], v[96:99], v190, v190 op_sel_hi:[0,0,0]
	s_barrier
	s_add_i32 s26, s34, s3
	v_lshl_add_u64 v[172:173], v[172:173], 0, s[16:17]
	s_mov_b32 m0, s26
	ds_read_b128 v[198:201], v193 offset:49152
	ds_read_b128 v[202:205], v193 offset:50176
	ds_read_b128 v[206:209], v193 offset:51200
	ds_read_b128 v[210:213], v193 offset:52224
	ds_read_b128 v[214:217], v193 offset:53248
	ds_read_b128 v[218:221], v193 offset:54272
	ds_read_b128 v[226:229], v193 offset:55296
	ds_read_b128 v[230:233], v193 offset:56320
	global_load_lds_dwordx4 v[172:173], off
	v_lshl_add_u64 v[170:171], v[170:171], 0, s[16:17]
	s_add_i32 m0, s26, 0x2000
	s_add_i32 s26, s35, s3
	global_load_lds_dwordx4 v[170:171], off
	v_lshl_add_u64 v[170:171], v[180:181], 0, s[16:17]
	s_mov_b32 m0, s26
	s_nop 0
	global_load_lds_dwordx4 v[170:171], off
	v_lshl_add_u64 v[170:171], v[178:179], 0, s[16:17]
	s_add_i32 m0, s26, 0x2000
	s_nop 0
	global_load_lds_dwordx4 v[170:171], off
	v_lshl_add_u64 v[170:171], v[174:175], 0, s[16:17]
	s_mov_b32 m0, s65
	s_nop 0
	global_load_lds_dwordx4 v[170:171], off
	v_lshl_add_u64 v[170:171], v[176:177], 0, s[16:17]
	s_mov_b32 m0, s66
	s_nop 0
	global_load_lds_dwordx4 v[170:171], off
	s_waitcnt vmcnt(8)
	s_waitcnt lgkmcnt(0)
	s_barrier
	s_waitcnt lgkmcnt(0)
	v_mfma_scale_f32_16x16x128_f8f6f4 v[92:95], v[0:7], v[198:205], v[92:95], v190, v190 op_sel_hi:[0,0,0]
	v_mfma_scale_f32_16x16x128_f8f6f4 v[88:91], v[8:15], v[198:205], v[88:91], v190, v190 op_sel_hi:[0,0,0]
	v_mfma_scale_f32_16x16x128_f8f6f4 v[76:79], v[0:7], v[206:213], v[76:79], v190, v190 op_sel_hi:[0,0,0]
	v_mfma_scale_f32_16x16x128_f8f6f4 v[72:75], v[8:15], v[206:213], v[72:75], v190, v190 op_sel_hi:[0,0,0]
	v_mfma_scale_f32_16x16x128_f8f6f4 v[60:63], v[0:7], v[214:221], v[60:63], v190, v190 op_sel_hi:[0,0,0]
	v_mfma_scale_f32_16x16x128_f8f6f4 v[56:59], v[8:15], v[214:221], v[56:59], v190, v190 op_sel_hi:[0,0,0]
	v_mfma_scale_f32_16x16x128_f8f6f4 v[44:47], v[0:7], v[226:233], v[44:47], v190, v190 op_sel_hi:[0,0,0]
	v_mfma_scale_f32_16x16x128_f8f6f4 v[40:43], v[8:15], v[226:233], v[40:43], v190, v190 op_sel_hi:[0,0,0]
	v_mfma_scale_f32_16x16x128_f8f6f4 v[84:87], v[16:23], v[198:205], v[84:87], v190, v190 op_sel_hi:[0,0,0]
	v_mfma_scale_f32_16x16x128_f8f6f4 v[80:83], v[24:31], v[198:205], v[80:83], v190, v190 op_sel_hi:[0,0,0]
	v_mfma_scale_f32_16x16x128_f8f6f4 v[68:71], v[16:23], v[206:213], v[68:71], v190, v190 op_sel_hi:[0,0,0]
	v_mfma_scale_f32_16x16x128_f8f6f4 v[64:67], v[24:31], v[206:213], v[64:67], v190, v190 op_sel_hi:[0,0,0]
	v_mfma_scale_f32_16x16x128_f8f6f4 v[52:55], v[16:23], v[214:221], v[52:55], v190, v190 op_sel_hi:[0,0,0]
	v_mfma_scale_f32_16x16x128_f8f6f4 v[48:51], v[24:31], v[214:221], v[48:51], v190, v190 op_sel_hi:[0,0,0]
	v_mfma_scale_f32_16x16x128_f8f6f4 v[36:39], v[16:23], v[226:233], v[36:39], v190, v190 op_sel_hi:[0,0,0]
	v_mfma_scale_f32_16x16x128_f8f6f4 v[32:35], v[24:31], v[226:233], v[32:35], v190, v190 op_sel_hi:[0,0,0]
	s_barrier
	s_add_i32 s77, s77, 2
	s_add_u32 s28, s28, 0x100
	s_addc_u32 s29, s29, 0
	s_cmp_gt_u32 s77, 41
	s_cbranch_scc1 .LBB0_1261
	v_mov_b32_e32 v172, v194
	v_mov_b32_e32 v160, v195
	v_mov_b32_e32 v174, v196
	v_mov_b32_e32 v170, v197
	s_mov_b64 s[26:27], s[30:31]
	s_branch .LBB0_1257

.LBB0_1356:
	ds_read_b128 v[144:147], v191
	ds_read_b128 v[148:151], v191 offset:1024
	ds_read_b128 v[152:155], v191 offset:2048
	ds_read_b128 v[156:159], v191 offset:3072
	ds_read_b128 v[160:163], v192
	ds_read_b128 v[164:167], v192 offset:1024
	ds_read_b128 v[168:171], v192 offset:2048
	ds_read_b128 v[172:175], v192 offset:3072
	s_add_u32 s36, s34, 0xfff80080
	s_addc_u32 s37, s35, -1
	s_cmp_eq_u32 s64, 28
	s_cselect_b32 s39, s9, s37
	s_cselect_b32 s38, s25, s36
	s_cselect_b32 s37, s23, s63
	s_cselect_b32 s36, s31, s62
	v_lshl_add_u64 v[216:217], s[34:35], 0, v[136:137]
	s_add_i32 m0, s42, 0xc000
	ds_read_b128 v[176:179], v193
	ds_read_b128 v[180:183], v193 offset:1024
	ds_read_b128 v[184:187], v193 offset:2048
	ds_read_b128 v[196:199], v193 offset:3072
	ds_read_b128 v[200:203], v193 offset:4096
	ds_read_b128 v[204:207], v193 offset:5120
	ds_read_b128 v[208:211], v193 offset:6144
	ds_read_b128 v[212:215], v193 offset:7168
	global_load_lds_dwordx4 v[216:217], off
	v_lshl_add_u64 v[216:217], s[34:35], 0, v[138:139]
	s_add_i32 m0, s42, 0xe000
	s_nop 0
	global_load_lds_dwordx4 v[216:217], off
	s_waitcnt vmcnt(8)
	s_waitcnt lgkmcnt(0)
	s_barrier
	s_waitcnt lgkmcnt(0)
	v_mfma_f32_16x16x32_bf16 v[124:127], v[144:147], v[176:179], v[124:127]
	v_mfma_f32_16x16x32_bf16 v[120:123], v[152:155], v[176:179], v[120:123]
	v_mfma_f32_16x16x32_bf16 v[108:111], v[144:147], v[184:187], v[108:111]
	v_mfma_f32_16x16x32_bf16 v[104:107], v[152:155], v[184:187], v[104:107]
	v_mfma_f32_16x16x32_bf16 v[92:95], v[144:147], v[200:203], v[92:95]
	v_mfma_f32_16x16x32_bf16 v[88:91], v[152:155], v[200:203], v[88:91]
	v_mfma_f32_16x16x32_bf16 v[76:79], v[144:147], v[208:211], v[76:79]
	v_mfma_f32_16x16x32_bf16 v[72:75], v[152:155], v[208:211], v[72:75]
	v_mfma_f32_16x16x32_bf16 v[124:127], v[148:151], v[180:183], v[124:127]
	v_mfma_f32_16x16x32_bf16 v[120:123], v[156:159], v[180:183], v[120:123]
	v_mfma_f32_16x16x32_bf16 v[108:111], v[148:151], v[196:199], v[108:111]
	v_mfma_f32_16x16x32_bf16 v[104:107], v[156:159], v[196:199], v[104:107]
	v_mfma_f32_16x16x32_bf16 v[92:95], v[148:151], v[204:207], v[92:95]
	v_mfma_f32_16x16x32_bf16 v[88:91], v[156:159], v[204:207], v[88:91]
	v_mfma_f32_16x16x32_bf16 v[76:79], v[148:151], v[212:215], v[76:79]
	v_mfma_f32_16x16x32_bf16 v[72:75], v[156:159], v[212:215], v[72:75]
	v_mfma_f32_16x16x32_bf16 v[116:119], v[160:163], v[176:179], v[116:119]
	v_mfma_f32_16x16x32_bf16 v[112:115], v[168:171], v[176:179], v[112:115]
	v_mfma_f32_16x16x32_bf16 v[100:103], v[160:163], v[184:187], v[100:103]
	v_mfma_f32_16x16x32_bf16 v[96:99], v[168:171], v[184:187], v[96:99]
	v_mfma_f32_16x16x32_bf16 v[84:87], v[160:163], v[200:203], v[84:87]
	v_mfma_f32_16x16x32_bf16 v[80:83], v[168:171], v[200:203], v[80:83]
	v_mfma_f32_16x16x32_bf16 v[68:71], v[160:163], v[208:211], v[68:71]
	v_mfma_f32_16x16x32_bf16 v[64:67], v[168:171], v[208:211], v[64:67]
	v_mfma_f32_16x16x32_bf16 v[116:119], v[164:167], v[180:183], v[116:119]
	v_mfma_f32_16x16x32_bf16 v[112:115], v[172:175], v[180:183], v[112:115]
	v_mfma_f32_16x16x32_bf16 v[100:103], v[164:167], v[196:199], v[100:103]
	v_mfma_f32_16x16x32_bf16 v[96:99], v[172:175], v[196:199], v[96:99]
	v_mfma_f32_16x16x32_bf16 v[84:87], v[164:167], v[204:207], v[84:87]
	v_mfma_f32_16x16x32_bf16 v[80:83], v[172:175], v[204:207], v[80:83]
	v_mfma_f32_16x16x32_bf16 v[68:71], v[164:167], v[212:215], v[68:71]
	v_mfma_f32_16x16x32_bf16 v[64:67], v[172:175], v[212:215], v[64:67]
	s_barrier
	s_add_i32 s65, s57, s3
	v_lshl_add_u64 v[216:217], s[36:37], 0, v[130:131]
	s_mov_b32 m0, s65
	ds_read_b128 v[176:179], v193 offset:16384
	ds_read_b128 v[180:183], v193 offset:17408
	ds_read_b128 v[184:187], v193 offset:18432
	ds_read_b128 v[196:199], v193 offset:19456
	ds_read_b128 v[200:203], v193 offset:20480
	ds_read_b128 v[204:207], v193 offset:21504
	ds_read_b128 v[208:211], v193 offset:22528
	ds_read_b128 v[212:215], v193 offset:23552
	global_load_lds_dwordx4 v[216:217], off
	s_add_i32 m0, s65, 0x2000
	s_add_u32 s66, s36, 0x80000
	v_lshl_add_u64 v[218:219], s[36:37], 0, v[134:135]
	s_addc_u32 s67, s37, 0
	s_add_i32 s65, s60, s3
	global_load_lds_dwordx4 v[218:219], off
	v_lshl_add_u64 v[220:221], s[66:67], 0, v[130:131]
	s_mov_b32 m0, s65
	v_lshl_add_u64 v[222:223], s[38:39], 0, v[132:133]
	global_load_lds_dwordx4 v[220:221], off
	v_lshl_add_u64 v[220:221], s[66:67], 0, v[134:135]
	s_add_i32 m0, s65, 0x2000
	s_nop 0
	global_load_lds_dwordx4 v[220:221], off
	v_lshl_add_u64 v[220:221], s[38:39], 0, v[128:129]
	s_mov_b32 m0, s42
	s_nop 0
	global_load_lds_dwordx4 v[220:221], off
	s_mov_b32 m0, s43
	s_nop 0
	global_load_lds_dwordx4 v[222:223], off
	s_waitcnt vmcnt(8)
	s_waitcnt lgkmcnt(0)
	s_barrier
	s_waitcnt lgkmcnt(0)
	v_mfma_f32_16x16x32_bf16 v[60:63], v[144:147], v[176:179], v[60:63]
	v_mfma_f32_16x16x32_bf16 v[56:59], v[152:155], v[176:179], v[56:59]
	v_mfma_f32_16x16x32_bf16 v[44:47], v[144:147], v[184:187], v[44:47]
	v_mfma_f32_16x16x32_bf16 v[40:43], v[152:155], v[184:187], v[40:43]
	v_mfma_f32_16x16x32_bf16 v[28:31], v[144:147], v[200:203], v[28:31]
	v_mfma_f32_16x16x32_bf16 v[24:27], v[152:155], v[200:203], v[24:27]
	v_mfma_f32_16x16x32_bf16 v[12:15], v[144:147], v[208:211], v[12:15]
	v_mfma_f32_16x16x32_bf16 v[8:11], v[152:155], v[208:211], v[8:11]
	v_mfma_f32_16x16x32_bf16 v[60:63], v[148:151], v[180:183], v[60:63]
	v_mfma_f32_16x16x32_bf16 v[56:59], v[156:159], v[180:183], v[56:59]
	v_mfma_f32_16x16x32_bf16 v[44:47], v[148:151], v[196:199], v[44:47]
	v_mfma_f32_16x16x32_bf16 v[40:43], v[156:159], v[196:199], v[40:43]
	v_mfma_f32_16x16x32_bf16 v[28:31], v[148:151], v[204:207], v[28:31]
	v_mfma_f32_16x16x32_bf16 v[24:27], v[156:159], v[204:207], v[24:27]
	v_mfma_f32_16x16x32_bf16 v[12:15], v[148:151], v[212:215], v[12:15]
	v_mfma_f32_16x16x32_bf16 v[8:11], v[156:159], v[212:215], v[8:11]
	v_mfma_f32_16x16x32_bf16 v[52:55], v[160:163], v[176:179], v[52:55]
	v_mfma_f32_16x16x32_bf16 v[48:51], v[168:171], v[176:179], v[48:51]
	v_mfma_f32_16x16x32_bf16 v[36:39], v[160:163], v[184:187], v[36:39]
	v_mfma_f32_16x16x32_bf16 v[32:35], v[168:171], v[184:187], v[32:35]
	v_mfma_f32_16x16x32_bf16 v[20:23], v[160:163], v[200:203], v[20:23]
	v_mfma_f32_16x16x32_bf16 v[16:19], v[168:171], v[200:203], v[16:19]
	v_mfma_f32_16x16x32_bf16 v[4:7], v[160:163], v[208:211], v[4:7]
	v_mfma_f32_16x16x32_bf16 v[0:3], v[168:171], v[208:211], v[0:3]
	v_mfma_f32_16x16x32_bf16 v[52:55], v[164:167], v[180:183], v[52:55]
	v_mfma_f32_16x16x32_bf16 v[48:51], v[172:175], v[180:183], v[48:51]
	v_mfma_f32_16x16x32_bf16 v[36:39], v[164:167], v[196:199], v[36:39]
	v_mfma_f32_16x16x32_bf16 v[32:35], v[172:175], v[196:199], v[32:35]
	v_mfma_f32_16x16x32_bf16 v[20:23], v[164:167], v[204:207], v[20:23]
	v_mfma_f32_16x16x32_bf16 v[16:19], v[172:175], v[204:207], v[16:19]
	v_mfma_f32_16x16x32_bf16 v[4:7], v[164:167], v[212:215], v[4:7]
	v_mfma_f32_16x16x32_bf16 v[0:3], v[172:175], v[212:215], v[0:3]
	s_barrier
	s_add_i32 s65, 0, 0x18000
	s_add_i32 s66, 0, 0x1c000
	v_add_u32_e32 v156, s65, v189
	v_add_u32_e32 v172, s66, v189
	ds_read_b128 v[144:147], v156
	ds_read_b128 v[148:151], v156 offset:1024
	ds_read_b128 v[152:155], v156 offset:2048
	ds_read_b128 v[156:159], v156 offset:3072
	ds_read_b128 v[160:163], v172
	ds_read_b128 v[164:167], v172 offset:1024
	ds_read_b128 v[168:171], v172 offset:2048
	ds_read_b128 v[172:175], v172 offset:3072
	s_add_u32 s38, s38, 0x80000
	s_addc_u32 s39, s39, 0
	s_mov_b32 m0, s44
	v_lshl_add_u64 v[224:225], s[38:39], 0, v[128:129]
	ds_read_b128 v[176:179], v193 offset:32768
	ds_read_b128 v[180:183], v193 offset:33792
	ds_read_b128 v[184:187], v193 offset:34816
	ds_read_b128 v[196:199], v193 offset:35840
	ds_read_b128 v[200:203], v193 offset:36864
	ds_read_b128 v[204:207], v193 offset:37888
	ds_read_b128 v[208:211], v193 offset:38912
	ds_read_b128 v[212:215], v193 offset:39936
	global_load_lds_dwordx4 v[224:225], off
	v_lshl_add_u64 v[224:225], s[38:39], 0, v[132:133]
	s_mov_b32 m0, s45
	s_nop 0
	global_load_lds_dwordx4 v[224:225], off
	s_waitcnt vmcnt(8)
	s_waitcnt lgkmcnt(0)
	s_barrier
	s_waitcnt lgkmcnt(0)
	v_mfma_f32_16x16x32_bf16 v[124:127], v[144:147], v[176:179], v[124:127]
	v_mfma_f32_16x16x32_bf16 v[120:123], v[152:155], v[176:179], v[120:123]
	v_mfma_f32_16x16x32_bf16 v[108:111], v[144:147], v[184:187], v[108:111]
	v_mfma_f32_16x16x32_bf16 v[104:107], v[152:155], v[184:187], v[104:107]
	v_mfma_f32_16x16x32_bf16 v[92:95], v[144:147], v[200:203], v[92:95]
	v_mfma_f32_16x16x32_bf16 v[88:91], v[152:155], v[200:203], v[88:91]
	v_mfma_f32_16x16x32_bf16 v[76:79], v[144:147], v[208:211], v[76:79]
	v_mfma_f32_16x16x32_bf16 v[72:75], v[152:155], v[208:211], v[72:75]
	v_mfma_f32_16x16x32_bf16 v[124:127], v[148:151], v[180:183], v[124:127]
	v_mfma_f32_16x16x32_bf16 v[120:123], v[156:159], v[180:183], v[120:123]
	v_mfma_f32_16x16x32_bf16 v[108:111], v[148:151], v[196:199], v[108:111]
	v_mfma_f32_16x16x32_bf16 v[104:107], v[156:159], v[196:199], v[104:107]
	v_mfma_f32_16x16x32_bf16 v[92:95], v[148:151], v[204:207], v[92:95]
	v_mfma_f32_16x16x32_bf16 v[88:91], v[156:159], v[204:207], v[88:91]
	v_mfma_f32_16x16x32_bf16 v[76:79], v[148:151], v[212:215], v[76:79]
	v_mfma_f32_16x16x32_bf16 v[72:75], v[156:159], v[212:215], v[72:75]
	v_mfma_f32_16x16x32_bf16 v[116:119], v[160:163], v[176:179], v[116:119]
	v_mfma_f32_16x16x32_bf16 v[112:115], v[168:171], v[176:179], v[112:115]
	v_mfma_f32_16x16x32_bf16 v[100:103], v[160:163], v[184:187], v[100:103]
	v_mfma_f32_16x16x32_bf16 v[96:99], v[168:171], v[184:187], v[96:99]
	v_mfma_f32_16x16x32_bf16 v[84:87], v[160:163], v[200:203], v[84:87]
	v_mfma_f32_16x16x32_bf16 v[80:83], v[168:171], v[200:203], v[80:83]
	v_mfma_f32_16x16x32_bf16 v[68:71], v[160:163], v[208:211], v[68:71]
	v_mfma_f32_16x16x32_bf16 v[64:67], v[168:171], v[208:211], v[64:67]
	v_mfma_f32_16x16x32_bf16 v[116:119], v[164:167], v[180:183], v[116:119]
	v_mfma_f32_16x16x32_bf16 v[112:115], v[172:175], v[180:183], v[112:115]
	v_mfma_f32_16x16x32_bf16 v[100:103], v[164:167], v[196:199], v[100:103]
	v_mfma_f32_16x16x32_bf16 v[96:99], v[172:175], v[196:199], v[96:99]
	v_mfma_f32_16x16x32_bf16 v[84:87], v[164:167], v[204:207], v[84:87]
	v_mfma_f32_16x16x32_bf16 v[80:83], v[172:175], v[204:207], v[80:83]
	v_mfma_f32_16x16x32_bf16 v[68:71], v[164:167], v[212:215], v[68:71]
	v_mfma_f32_16x16x32_bf16 v[64:67], v[172:175], v[212:215], v[64:67]
	s_barrier
	s_add_i32 s38, s65, s3
	v_lshl_add_u64 v[216:217], v[216:217], 0, s[18:19]
	s_mov_b32 m0, s38
	ds_read_b128 v[176:179], v193 offset:49152
	ds_read_b128 v[180:183], v193 offset:50176
	ds_read_b128 v[184:187], v193 offset:51200
	ds_read_b128 v[196:199], v193 offset:52224
	ds_read_b128 v[200:203], v193 offset:53248
	ds_read_b128 v[204:207], v193 offset:54272
	ds_read_b128 v[208:211], v193 offset:55296
	ds_read_b128 v[212:215], v193 offset:56320
	global_load_lds_dwordx4 v[216:217], off
	s_add_i32 m0, s38, 0x2000
	s_add_u32 s36, s36, 0x80080
	v_lshl_add_u64 v[216:217], v[218:219], 0, s[18:19]
	s_addc_u32 s37, s37, 0
	s_add_i32 s38, s66, s3
	global_load_lds_dwordx4 v[216:217], off
	v_lshl_add_u64 v[216:217], s[36:37], 0, v[130:131]
	s_mov_b32 m0, s38
	s_nop 0
	global_load_lds_dwordx4 v[216:217], off
	v_lshl_add_u64 v[216:217], s[36:37], 0, v[134:135]
	s_add_i32 m0, s38, 0x2000
	s_nop 0
	global_load_lds_dwordx4 v[216:217], off
	v_lshl_add_u64 v[216:217], v[220:221], 0, s[18:19]
	s_mov_b32 m0, s54
	s_nop 0
	global_load_lds_dwordx4 v[216:217], off
	v_lshl_add_u64 v[216:217], v[222:223], 0, s[18:19]
	s_mov_b32 m0, s55
	s_nop 0
	global_load_lds_dwordx4 v[216:217], off
	s_waitcnt vmcnt(8)
	s_waitcnt lgkmcnt(0)
	s_barrier
	s_waitcnt lgkmcnt(0)
	v_mfma_f32_16x16x32_bf16 v[60:63], v[144:147], v[176:179], v[60:63]
	v_mfma_f32_16x16x32_bf16 v[56:59], v[152:155], v[176:179], v[56:59]
	v_mfma_f32_16x16x32_bf16 v[44:47], v[144:147], v[184:187], v[44:47]
	v_mfma_f32_16x16x32_bf16 v[40:43], v[152:155], v[184:187], v[40:43]
	v_mfma_f32_16x16x32_bf16 v[28:31], v[144:147], v[200:203], v[28:31]
	v_mfma_f32_16x16x32_bf16 v[24:27], v[152:155], v[200:203], v[24:27]
	v_mfma_f32_16x16x32_bf16 v[12:15], v[144:147], v[208:211], v[12:15]
	v_mfma_f32_16x16x32_bf16 v[8:11], v[152:155], v[208:211], v[8:11]
	v_mfma_f32_16x16x32_bf16 v[60:63], v[148:151], v[180:183], v[60:63]
	v_mfma_f32_16x16x32_bf16 v[56:59], v[156:159], v[180:183], v[56:59]
	v_mfma_f32_16x16x32_bf16 v[44:47], v[148:151], v[196:199], v[44:47]
	v_mfma_f32_16x16x32_bf16 v[40:43], v[156:159], v[196:199], v[40:43]
	v_mfma_f32_16x16x32_bf16 v[28:31], v[148:151], v[204:207], v[28:31]
	v_mfma_f32_16x16x32_bf16 v[24:27], v[156:159], v[204:207], v[24:27]
	v_mfma_f32_16x16x32_bf16 v[12:15], v[148:151], v[212:215], v[12:15]
	v_mfma_f32_16x16x32_bf16 v[8:11], v[156:159], v[212:215], v[8:11]
	v_mfma_f32_16x16x32_bf16 v[52:55], v[160:163], v[176:179], v[52:55]
	v_mfma_f32_16x16x32_bf16 v[48:51], v[168:171], v[176:179], v[48:51]
	v_mfma_f32_16x16x32_bf16 v[36:39], v[160:163], v[184:187], v[36:39]
	v_mfma_f32_16x16x32_bf16 v[32:35], v[168:171], v[184:187], v[32:35]
	v_mfma_f32_16x16x32_bf16 v[20:23], v[160:163], v[200:203], v[20:23]
	v_mfma_f32_16x16x32_bf16 v[16:19], v[168:171], v[200:203], v[16:19]
	v_mfma_f32_16x16x32_bf16 v[4:7], v[160:163], v[208:211], v[4:7]
	v_mfma_f32_16x16x32_bf16 v[0:3], v[168:171], v[208:211], v[0:3]
	v_mfma_f32_16x16x32_bf16 v[52:55], v[164:167], v[180:183], v[52:55]
	v_mfma_f32_16x16x32_bf16 v[48:51], v[172:175], v[180:183], v[48:51]
	v_mfma_f32_16x16x32_bf16 v[36:39], v[164:167], v[196:199], v[36:39]
	v_mfma_f32_16x16x32_bf16 v[32:35], v[172:175], v[196:199], v[32:35]
	v_mfma_f32_16x16x32_bf16 v[20:23], v[164:167], v[204:207], v[20:23]
	v_mfma_f32_16x16x32_bf16 v[16:19], v[172:175], v[204:207], v[16:19]
	v_mfma_f32_16x16x32_bf16 v[4:7], v[164:167], v[212:215], v[4:7]
	v_mfma_f32_16x16x32_bf16 v[0:3], v[172:175], v[212:215], v[0:3]
	s_barrier
	s_add_i32 s64, s64, 2
	s_add_u32 s34, s34, 0x100
	s_addc_u32 s35, s35, 0
	s_add_u32 s62, s62, 0x100
	s_addc_u32 s63, s63, 0
	s_cmp_gt_u32 s64, 29
	s_cbranch_scc0 .LBB0_1356
	s_and_b64 vcc, exec, s[20:21]
	s_cbranch_vccz .LBB0_1359
	s_barrier
